# adds: per-row rstd kept in registers across tiles of a GEMM phase (ss loads and conversion skipped when the row block is unchanged)
# baseline (speedup 1.0000x reference)
;     __host__ __device__ bool next(int i, Unit& u) const {
;         const long L = (long)i * G + c; if (L >= nwg) return false;
;         int wgid = (int)L; { const int q = nwg / NXCD, r = nwg % NXCD, xcd = wgid % NXCD, off = wgid / NXCD; wgid = (xcd < r ? xcd * (q + 1) : r * (q + 1) + (xcd - r) * q) + off; }
;         const int nig = WGM * nN, gid = wgid / nig, fm = gid * WGM, gsz = (nM - fm) < WGM ? (nM - fm) : WGM;
;         u.pm = fm + ((wgid % nig) % gsz); u.pn = (wgid % nig) / gsz; return true;
.LBB0_343:
	v_writelane_b32 v250, -1, 50
	v_writelane_b32 v250, 0, 51
	s_mul_i32 s60, s2, s87
	s_waitcnt vmcnt(0)
	v_mov_b32_e32 v8, v226
	s_cmp_lt_i32 s92, s60
	s_cselect_b64 s[42:43], -1, 0
	s_cmp_ge_i32 s92, s60
	v_readfirstlane_b32 s34, v8
	s_cbranch_scc1 .LBB0_345
	s_lshl_b32 s0, s2, 3
	v_cvt_f32_u32_e32 v0, s0
	s_lshr_b32 s1, s60, 3
	v_readlane_b32 s40, v251, 23
	s_or_b32 s1, s1, s40
	v_rcp_iflag_f32_e32 v0, v0
	s_sub_i32 s40, 0, s0
	v_readlane_b32 s41, v251, 22
	s_mul_i32 s1, s1, s41
	v_mul_f32_e32 v0, 0x4f7ffffe, v0
	v_cvt_u32_f32_e32 v0, v0
	v_readlane_b32 s41, v251, 14
	s_add_i32 s1, s1, s41
	s_abs_i32 s46, s1
	v_readfirstlane_b32 s47, v0
	s_mul_i32 s40, s40, s47
	s_mul_hi_u32 s40, s47, s40
	s_add_i32 s47, s47, s40
	s_mul_hi_u32 s40, s46, s47
	s_mul_i32 s47, s40, s0
	s_sub_i32 s46, s46, s47
	s_ashr_i32 s41, s1, 31
	s_add_i32 s55, s40, 1
	s_sub_i32 s47, s46, s0
	s_cmp_ge_u32 s46, s0
	s_cselect_b32 s40, s55, s40
	s_cselect_b32 s46, s47, s46
	s_add_i32 s47, s40, 1
	s_cmp_ge_u32 s46, s0
	s_cselect_b32 s40, s47, s40
	s_xor_b32 s40, s40, s41
	s_sub_i32 s40, s40, s41
	s_lshl_b32 s41, s40, 3
	s_sub_i32 s46, s87, s41
	s_min_i32 s46, s46, 8
	s_mul_i32 s40, s40, s0
	s_sext_i32_i16 s0, s46
	v_cvt_f32_i32_e32 v0, s0
	s_sub_i32 s40, s1, s40
	s_sext_i32_i16 s1, s40
	v_cvt_f32_i32_e32 v1, s1
	v_rcp_iflag_f32_e32 v2, v0
	s_xor_b32 s0, s1, s0
	s_ashr_i32 s0, s0, 30
	s_or_b32 s47, s0, 1
	v_mul_f32_e32 v2, v1, v2
	v_trunc_f32_e32 v2, v2
	v_fma_f32 v1, -v2, v0, v1
	v_cvt_i32_f32_e32 v2, v2
	v_cmp_ge_f32_e64 s[0:1], |v1|, |v0|
	s_and_b64 s[0:1], s[0:1], exec
	s_cselect_b32 s0, s47, 0
	v_readfirstlane_b32 s1, v2
	s_add_i32 s1, s1, s0
	s_sext_i32_i16 s0, s1
	s_mul_i32 s1, s1, s46
	s_sub_i32 s1, s40, s1
	s_sext_i32_i16 s1, s1
	s_add_i32 s40, s41, s1

;     __device__ __forceinline__ void operator()(const f32x4 (&acc)[2][2][4][2], const Unit& u, int wr, int wc, int fr, int fq) const {
;         const int row0 = u.pm * BM + wr * 64 + fr;
;         const int colt = u.pn * BM;
;         if (mode == 0) {
;     ...
;                 const int r = row0 + ai * HALF + m * 16;
;                 const float rs = __builtin_amdgcn_rsqf((float)ss[r] * (1.0f / 1048576.0f) * (1.0f / 1024.0f) + EPS);
.LBB0_357:
	s_lshl_b32 s69, s40, 8
	s_add_i32 s69, s69, s98
	v_or_b32_e32 v160, s69, v155
	s_lshl_b32 s76, s0, 8
	s_mov_b64 s[40:41], -1
	s_andn2_b64 vcc, exec, s[64:65]
	v_ashrrev_i32_e32 v161, 31, v160
	v_readlane_b32 s34, v250, 50
	s_nop 1
	s_cmp_eq_u32 s34, s69
	s_cbranch_scc1 .Lss_have
	v_lshl_add_u64 v[222:223], v[160:161], 3, s[48:49]
	global_load_dwordx2 v[192:193], v[222:223], off
	global_load_dwordx2 v[194:195], v[222:223], off offset:128
	global_load_dwordx2 v[196:197], v[222:223], off offset:256
	global_load_dwordx2 v[198:199], v[222:223], off offset:384
	global_load_dwordx2 v[200:201], v[222:223], off offset:1024
	global_load_dwordx2 v[202:203], v[222:223], off offset:1152
	global_load_dwordx2 v[204:205], v[222:223], off offset:1280
	global_load_dwordx2 v[206:207], v[222:223], off offset:1408
	v_writelane_b32 v250, s69, 50
	v_writelane_b32 v250, 1, 51
.Lss_have:
	s_cbranch_vccz .LBB0_360
	s_and_b64 vcc, exec, s[40:41]
	s_cbranch_vccnz .LBB0_425

;     __device__ __forceinline__ void operator()(const f32x4 (&acc)[2][2][4][2], const Unit& u, int wr, int wc, int fr, int fq) const {
;     ...
;                 const int r = row0 + ai * HALF + m * 16;
;                 const float rs = __builtin_amdgcn_rsqf((float)ss[r] * (1.0f / 1048576.0f) * (1.0f / 1024.0f) + EPS);
;                 bf16_t* rowp = O + (size_t)r * ldc + colt + wc * 32 + 8 * fq;
; #pragma unroll
;                 for (int bj = 0; bj < 2; ++bj) { f32x4 v0 = acc[ai][bj][m][0] * rs, v1 = acc[ai][bj][m][1] * rs;
;                     if (mode == 2) {
; #pragma unroll
;                         for (int e = 0; e < 4; ++e) { float a = fmaxf(v0[e], 0.f), b = fmaxf(v1[e], 0.f); v0[e] = a * a; v1[e] = b * b; } }
.LBB0_360:
	v_lshl_add_u64 v[80:81], v[160:161], 3, s[48:49]
	s_and_b64 vcc, exec, s[50:51]
	s_waitcnt vmcnt(0)
	v_readlane_b32 s34, v250, 51
	s_nop 1
	s_cmp_eq_u32 s34, 0
	s_cbranch_scc1 .Lss_nc_a
	v_cvt_f32_u32_e32 v223, v193
	v_cvt_f32_u32_e32 v222, v192
	v_fmamk_f32 v222, v223, 0x4f800000, v222
	v_fmamk_f32 v222, v222, 0x30800000, v229
	v_rsq_f32_e32 v242, v222
	v_cvt_f32_u32_e32 v223, v195
	v_cvt_f32_u32_e32 v222, v194
	v_fmamk_f32 v222, v223, 0x4f800000, v222
	v_fmamk_f32 v222, v222, 0x30800000, v229
	v_rsq_f32_e32 v243, v222
	v_cvt_f32_u32_e32 v223, v197
	v_cvt_f32_u32_e32 v222, v196
	v_fmamk_f32 v222, v223, 0x4f800000, v222
	v_fmamk_f32 v222, v222, 0x30800000, v229
	v_rsq_f32_e32 v244, v222
	v_cvt_f32_u32_e32 v223, v199
	v_cvt_f32_u32_e32 v222, v198
	v_fmamk_f32 v222, v223, 0x4f800000, v222
	v_fmamk_f32 v222, v222, 0x30800000, v229
	v_rsq_f32_e32 v245, v222
	v_cvt_f32_u32_e32 v223, v201
	v_cvt_f32_u32_e32 v222, v200
	v_fmamk_f32 v222, v223, 0x4f800000, v222
	v_fmamk_f32 v222, v222, 0x30800000, v229
	v_rsq_f32_e32 v246, v222
	v_cvt_f32_u32_e32 v223, v203
	v_cvt_f32_u32_e32 v222, v202
	v_fmamk_f32 v222, v223, 0x4f800000, v222
	v_fmamk_f32 v222, v222, 0x30800000, v229
	v_rsq_f32_e32 v247, v222
	v_cvt_f32_u32_e32 v223, v205
	v_cvt_f32_u32_e32 v222, v204
	v_fmamk_f32 v222, v223, 0x4f800000, v222
	v_fmamk_f32 v222, v222, 0x30800000, v229
	v_rsq_f32_e32 v248, v222
	v_cvt_f32_u32_e32 v223, v207
	v_cvt_f32_u32_e32 v222, v206
	v_fmamk_f32 v222, v223, 0x4f800000, v222
	v_fmamk_f32 v222, v222, 0x30800000, v229
	v_rsq_f32_e32 v249, v222
	v_writelane_b32 v250, 0, 51
.Lss_nc_a:
	s_nop 1
	v_mov_b32_e32 v82, v242
	s_nop 0
	v_pk_mul_f32 v[86:87], v[144:145], v[82:83] op_sel_hi:[1,0]
	v_pk_mul_f32 v[90:91], v[142:143], v[82:83] op_sel_hi:[1,0]
	v_pk_mul_f32 v[88:89], v[140:141], v[82:83] op_sel_hi:[1,0]
	v_pk_mul_f32 v[92:93], v[138:139], v[82:83] op_sel_hi:[1,0]
	s_cbranch_vccz .LBB0_362
	v_max_f32_e32 v84, 0, v90
	v_max_f32_e32 v92, 0, v92
	v_max_f32_e32 v85, 0, v91
	v_max_f32_e32 v93, 0, v93
	v_max_f32_e32 v86, 0, v86
	v_max_f32_e32 v88, 0, v88
	v_max_f32_e32 v87, 0, v87
	v_max_f32_e32 v89, 0, v89
	v_pk_mul_f32 v[90:91], v[84:85], v[84:85]
	v_pk_mul_f32 v[86:87], v[86:87], v[86:87]
	v_pk_mul_f32 v[92:93], v[92:93], v[92:93]
	v_pk_mul_f32 v[88:89], v[88:89], v[88:89]

; __device__ __forceinline__ unsigned cvt_pk_bf16(float lo, float hi) { unsigned r; asm volatile("v_cvt_pk_bf16_f32 %0, %1, %2" : "=v"(r) : "v"(lo), "v"(hi)); return r; }
;     __device__ __forceinline__ void operator()(const f32x4 (&acc)[2][2][4][2], const Unit& u, int wr, int wc, int fr, int fq) const {
;     ...
;                 const float rs = __builtin_amdgcn_rsqf((float)ss[r] * (1.0f / 1048576.0f) * (1.0f / 1024.0f) + EPS);
;                 bf16_t* rowp = O + (size_t)r * ldc + colt + wc * 32 + 8 * fq;
; #pragma unroll
;                 for (int bj = 0; bj < 2; ++bj) { f32x4 v0 = acc[ai][bj][m][0] * rs, v1 = acc[ai][bj][m][1] * rs;
;                     if (mode == 2) {
; #pragma unroll
;                         for (int e = 0; e < 4; ++e) { float a = fmaxf(v0[e], 0.f), b = fmaxf(v1[e], 0.f); v0[e] = a * a; v1[e] = b * b; } }
;                     if (mode == 1 && colt >= 2048) {
; #pragma unroll
;                         for (int e = 0; e < 4; ++e) { v0[e] = __builtin_amdgcn_rcpf(1.0f + __builtin_amdgcn_exp2f(-1.4426950408889634f * v0[e])); v1[e] = __builtin_amdgcn_rcpf(1.0f + __builtin_amdgcn_exp2f(-1.4426950408889634f * v1[e])); } }
;                     u32x4 w; w.x = cvt_pk_bf16(v0[0], v0[1]); w.y = cvt_pk_bf16(v0[2], v0[3]); w.z = cvt_pk_bf16(v1[0], v1[1]); w.w = cvt_pk_bf16(v1[2], v1[3]);
;                     *(u32x4*)(rowp + bj * HALF) = w; }
.LBB0_368:
	v_cvt_pk_bf16_f32 v90, v90, v91
	v_cvt_pk_bf16_f32 v91, v86, v87
	v_cvt_pk_bf16_f32 v92, v82, v83
	v_cvt_pk_bf16_f32 v93, v88, v89
	global_store_dwordx4 v[84:85], v[90:93], off offset:256
	s_and_b64 vcc, exec, s[42:43]
	s_nop 1
	v_mov_b32_e32 v82, v243
	s_nop 0
	v_pk_mul_f32 v[86:87], v[128:129], v[82:83] op_sel_hi:[1,0]
	v_pk_mul_f32 v[90:91], v[126:127], v[82:83] op_sel_hi:[1,0]
	v_pk_mul_f32 v[88:89], v[124:125], v[82:83] op_sel_hi:[1,0]
	v_pk_mul_f32 v[92:93], v[122:123], v[82:83] op_sel_hi:[1,0]
	s_cbranch_vccnz .LBB0_370
	v_max_f32_e32 v84, 0, v90
	v_max_f32_e32 v92, 0, v92
	v_max_f32_e32 v85, 0, v91
	v_max_f32_e32 v93, 0, v93
	v_max_f32_e32 v86, 0, v86
	v_max_f32_e32 v88, 0, v88
	v_max_f32_e32 v87, 0, v87
	v_max_f32_e32 v89, 0, v89
	v_pk_mul_f32 v[90:91], v[84:85], v[84:85]
	v_pk_mul_f32 v[86:87], v[86:87], v[86:87]
	v_pk_mul_f32 v[92:93], v[92:93], v[92:93]
	v_pk_mul_f32 v[88:89], v[88:89], v[88:89]

; __device__ __forceinline__ unsigned cvt_pk_bf16(float lo, float hi) { unsigned r; asm volatile("v_cvt_pk_bf16_f32 %0, %1, %2" : "=v"(r) : "v"(lo), "v"(hi)); return r; }
;     __device__ __forceinline__ void operator()(const f32x4 (&acc)[2][2][4][2], const Unit& u, int wr, int wc, int fr, int fq) const {
;     ...
;                 const float rs = __builtin_amdgcn_rsqf((float)ss[r] * (1.0f / 1048576.0f) * (1.0f / 1024.0f) + EPS);
;                 bf16_t* rowp = O + (size_t)r * ldc + colt + wc * 32 + 8 * fq;
; #pragma unroll
;                 for (int bj = 0; bj < 2; ++bj) { f32x4 v0 = acc[ai][bj][m][0] * rs, v1 = acc[ai][bj][m][1] * rs;
;                     if (mode == 2) {
; #pragma unroll
;                         for (int e = 0; e < 4; ++e) { float a = fmaxf(v0[e], 0.f), b = fmaxf(v1[e], 0.f); v0[e] = a * a; v1[e] = b * b; } }
;                     if (mode == 1 && colt >= 2048) {
; #pragma unroll
;                         for (int e = 0; e < 4; ++e) { v0[e] = __builtin_amdgcn_rcpf(1.0f + __builtin_amdgcn_exp2f(-1.4426950408889634f * v0[e])); v1[e] = __builtin_amdgcn_rcpf(1.0f + __builtin_amdgcn_exp2f(-1.4426950408889634f * v1[e])); } }
;                     u32x4 w; w.x = cvt_pk_bf16(v0[0], v0[1]); w.y = cvt_pk_bf16(v0[2], v0[3]); w.z = cvt_pk_bf16(v1[0], v1[1]); w.w = cvt_pk_bf16(v1[2], v1[3]);
;                     *(u32x4*)(rowp + bj * HALF) = w; }
.LBB0_376:
	v_cvt_pk_bf16_f32 v90, v90, v91
	v_cvt_pk_bf16_f32 v91, v86, v87
	v_cvt_pk_bf16_f32 v92, v82, v83
	v_cvt_pk_bf16_f32 v93, v88, v89
	global_store_dwordx4 v[208:209], v[90:93], off offset:256
	v_lshl_add_u64 v[208:209], v[208:209], 0, v[210:211]
	s_and_b64 vcc, exec, s[42:43]
	s_nop 1
	v_mov_b32_e32 v82, v244
	s_nop 0
	v_pk_mul_f32 v[86:87], v[110:111], v[82:83] op_sel_hi:[1,0]
	v_pk_mul_f32 v[90:91], v[108:109], v[82:83] op_sel_hi:[1,0]
	v_pk_mul_f32 v[88:89], v[106:107], v[82:83] op_sel_hi:[1,0]
	v_pk_mul_f32 v[92:93], v[104:105], v[82:83] op_sel_hi:[1,0]
	s_cbranch_vccnz .LBB0_378
	v_max_f32_e32 v84, 0, v90
	v_max_f32_e32 v92, 0, v92
	v_max_f32_e32 v85, 0, v91
	v_max_f32_e32 v93, 0, v93
	v_max_f32_e32 v86, 0, v86
	v_max_f32_e32 v88, 0, v88
	v_max_f32_e32 v87, 0, v87
	v_max_f32_e32 v89, 0, v89
	v_pk_mul_f32 v[90:91], v[84:85], v[84:85]
	v_pk_mul_f32 v[86:87], v[86:87], v[86:87]
	v_pk_mul_f32 v[92:93], v[92:93], v[92:93]
	v_pk_mul_f32 v[88:89], v[88:89], v[88:89]

; __device__ __forceinline__ unsigned cvt_pk_bf16(float lo, float hi) { unsigned r; asm volatile("v_cvt_pk_bf16_f32 %0, %1, %2" : "=v"(r) : "v"(lo), "v"(hi)); return r; }
;     __device__ __forceinline__ void operator()(const f32x4 (&acc)[2][2][4][2], const Unit& u, int wr, int wc, int fr, int fq) const {
;     ...
;                 const float rs = __builtin_amdgcn_rsqf((float)ss[r] * (1.0f / 1048576.0f) * (1.0f / 1024.0f) + EPS);
;                 bf16_t* rowp = O + (size_t)r * ldc + colt + wc * 32 + 8 * fq;
; #pragma unroll
;                 for (int bj = 0; bj < 2; ++bj) { f32x4 v0 = acc[ai][bj][m][0] * rs, v1 = acc[ai][bj][m][1] * rs;
;                     if (mode == 2) {
; #pragma unroll
;                         for (int e = 0; e < 4; ++e) { float a = fmaxf(v0[e], 0.f), b = fmaxf(v1[e], 0.f); v0[e] = a * a; v1[e] = b * b; } }
;                     if (mode == 1 && colt >= 2048) {
; #pragma unroll
;                         for (int e = 0; e < 4; ++e) { v0[e] = __builtin_amdgcn_rcpf(1.0f + __builtin_amdgcn_exp2f(-1.4426950408889634f * v0[e])); v1[e] = __builtin_amdgcn_rcpf(1.0f + __builtin_amdgcn_exp2f(-1.4426950408889634f * v1[e])); } }
;                     u32x4 w; w.x = cvt_pk_bf16(v0[0], v0[1]); w.y = cvt_pk_bf16(v0[2], v0[3]); w.z = cvt_pk_bf16(v1[0], v1[1]); w.w = cvt_pk_bf16(v1[2], v1[3]);
;                     *(u32x4*)(rowp + bj * HALF) = w; }
.LBB0_384:
	v_cvt_pk_bf16_f32 v90, v90, v91
	v_cvt_pk_bf16_f32 v91, v86, v87
	v_cvt_pk_bf16_f32 v92, v82, v83
	v_cvt_pk_bf16_f32 v93, v88, v89
	global_store_dwordx4 v[208:209], v[90:93], off offset:256
	v_lshl_add_u64 v[208:209], v[208:209], 0, v[210:211]
	s_and_b64 vcc, exec, s[42:43]
	s_nop 1
	v_mov_b32_e32 v82, v245
	s_nop 0
	v_pk_mul_f32 v[86:87], v[78:79], v[82:83] op_sel_hi:[1,0]
	v_pk_mul_f32 v[90:91], v[76:77], v[82:83] op_sel_hi:[1,0]
	v_pk_mul_f32 v[88:89], v[74:75], v[82:83] op_sel_hi:[1,0]
	v_pk_mul_f32 v[92:93], v[72:73], v[82:83] op_sel_hi:[1,0]
	s_cbranch_vccnz .LBB0_386
	v_max_f32_e32 v84, 0, v90
	v_max_f32_e32 v92, 0, v92
	v_max_f32_e32 v85, 0, v91
	v_max_f32_e32 v93, 0, v93
	v_max_f32_e32 v86, 0, v86
	v_max_f32_e32 v88, 0, v88
	v_max_f32_e32 v87, 0, v87
	v_max_f32_e32 v89, 0, v89
	v_pk_mul_f32 v[90:91], v[84:85], v[84:85]
	v_pk_mul_f32 v[86:87], v[86:87], v[86:87]
	v_pk_mul_f32 v[92:93], v[92:93], v[92:93]
	v_pk_mul_f32 v[88:89], v[88:89], v[88:89]

; __device__ __forceinline__ unsigned cvt_pk_bf16(float lo, float hi) { unsigned r; asm volatile("v_cvt_pk_bf16_f32 %0, %1, %2" : "=v"(r) : "v"(lo), "v"(hi)); return r; }
;     __device__ __forceinline__ void operator()(const f32x4 (&acc)[2][2][4][2], const Unit& u, int wr, int wc, int fr, int fq) const {
;     ...
;                 const float rs = __builtin_amdgcn_rsqf((float)ss[r] * (1.0f / 1048576.0f) * (1.0f / 1024.0f) + EPS);
;                 bf16_t* rowp = O + (size_t)r * ldc + colt + wc * 32 + 8 * fq;
; #pragma unroll
;                 for (int bj = 0; bj < 2; ++bj) { f32x4 v0 = acc[ai][bj][m][0] * rs, v1 = acc[ai][bj][m][1] * rs;
;                     if (mode == 2) {
; #pragma unroll
;                         for (int e = 0; e < 4; ++e) { float a = fmaxf(v0[e], 0.f), b = fmaxf(v1[e], 0.f); v0[e] = a * a; v1[e] = b * b; } }
;                     if (mode == 1 && colt >= 2048) {
; #pragma unroll
;                         for (int e = 0; e < 4; ++e) { v0[e] = __builtin_amdgcn_rcpf(1.0f + __builtin_amdgcn_exp2f(-1.4426950408889634f * v0[e])); v1[e] = __builtin_amdgcn_rcpf(1.0f + __builtin_amdgcn_exp2f(-1.4426950408889634f * v1[e])); } }
;                     u32x4 w; w.x = cvt_pk_bf16(v0[0], v0[1]); w.y = cvt_pk_bf16(v0[2], v0[3]); w.z = cvt_pk_bf16(v1[0], v1[1]); w.w = cvt_pk_bf16(v1[2], v1[3]);
;                     *(u32x4*)(rowp + bj * HALF) = w; }
.LBB0_392:
	v_cvt_pk_bf16_f32 v90, v90, v91
	v_cvt_pk_bf16_f32 v91, v86, v87
	v_cvt_pk_bf16_f32 v92, v82, v83
	v_cvt_pk_bf16_f32 v93, v88, v89
	global_store_dwordx4 v[208:209], v[90:93], off offset:256
	v_lshl_add_u64 v[208:209], v[208:209], 0, v[212:213]
	s_and_b64 vcc, exec, s[42:43]
	s_nop 1
	v_mov_b32_e32 v82, v246
	s_nop 0
	v_pk_mul_f32 v[86:87], v[62:63], v[82:83] op_sel_hi:[1,0]
	v_pk_mul_f32 v[90:91], v[60:61], v[82:83] op_sel_hi:[1,0]
	v_pk_mul_f32 v[88:89], v[58:59], v[82:83] op_sel_hi:[1,0]
	v_pk_mul_f32 v[92:93], v[56:57], v[82:83] op_sel_hi:[1,0]
	s_cbranch_vccnz .LBB0_394
	v_max_f32_e32 v84, 0, v90
	v_max_f32_e32 v92, 0, v92
	v_max_f32_e32 v85, 0, v91
	v_max_f32_e32 v93, 0, v93
	v_max_f32_e32 v86, 0, v86
	v_max_f32_e32 v88, 0, v88
	v_max_f32_e32 v87, 0, v87
	v_max_f32_e32 v89, 0, v89
	v_pk_mul_f32 v[90:91], v[84:85], v[84:85]
	v_pk_mul_f32 v[86:87], v[86:87], v[86:87]
	v_pk_mul_f32 v[92:93], v[92:93], v[92:93]
	v_pk_mul_f32 v[88:89], v[88:89], v[88:89]

; __device__ __forceinline__ unsigned cvt_pk_bf16(float lo, float hi) { unsigned r; asm volatile("v_cvt_pk_bf16_f32 %0, %1, %2" : "=v"(r) : "v"(lo), "v"(hi)); return r; }
;     __device__ __forceinline__ void operator()(const f32x4 (&acc)[2][2][4][2], const Unit& u, int wr, int wc, int fr, int fq) const {
;     ...
;                 const float rs = __builtin_amdgcn_rsqf((float)ss[r] * (1.0f / 1048576.0f) * (1.0f / 1024.0f) + EPS);
;                 bf16_t* rowp = O + (size_t)r * ldc + colt + wc * 32 + 8 * fq;
; #pragma unroll
;                 for (int bj = 0; bj < 2; ++bj) { f32x4 v0 = acc[ai][bj][m][0] * rs, v1 = acc[ai][bj][m][1] * rs;
;                     if (mode == 2) {
; #pragma unroll
;                         for (int e = 0; e < 4; ++e) { float a = fmaxf(v0[e], 0.f), b = fmaxf(v1[e], 0.f); v0[e] = a * a; v1[e] = b * b; } }
;                     if (mode == 1 && colt >= 2048) {
; #pragma unroll
;                         for (int e = 0; e < 4; ++e) { v0[e] = __builtin_amdgcn_rcpf(1.0f + __builtin_amdgcn_exp2f(-1.4426950408889634f * v0[e])); v1[e] = __builtin_amdgcn_rcpf(1.0f + __builtin_amdgcn_exp2f(-1.4426950408889634f * v1[e])); } }
;                     u32x4 w; w.x = cvt_pk_bf16(v0[0], v0[1]); w.y = cvt_pk_bf16(v0[2], v0[3]); w.z = cvt_pk_bf16(v1[0], v1[1]); w.w = cvt_pk_bf16(v1[2], v1[3]);
;                     *(u32x4*)(rowp + bj * HALF) = w; }
.LBB0_400:
	v_cvt_pk_bf16_f32 v90, v90, v91
	v_cvt_pk_bf16_f32 v91, v86, v87
	v_cvt_pk_bf16_f32 v92, v82, v83
	v_cvt_pk_bf16_f32 v93, v88, v89
	global_store_dwordx4 v[208:209], v[90:93], off offset:256
	v_lshl_add_u64 v[208:209], v[208:209], 0, v[210:211]
	s_and_b64 vcc, exec, s[42:43]
	s_nop 1
	v_mov_b32_e32 v82, v247
	s_nop 0
	v_pk_mul_f32 v[86:87], v[46:47], v[82:83] op_sel_hi:[1,0]
	v_pk_mul_f32 v[90:91], v[44:45], v[82:83] op_sel_hi:[1,0]
	v_pk_mul_f32 v[88:89], v[42:43], v[82:83] op_sel_hi:[1,0]
	v_pk_mul_f32 v[92:93], v[40:41], v[82:83] op_sel_hi:[1,0]
	s_cbranch_vccnz .LBB0_402
	v_max_f32_e32 v84, 0, v90
	v_max_f32_e32 v92, 0, v92
	v_max_f32_e32 v85, 0, v91
	v_max_f32_e32 v93, 0, v93
	v_max_f32_e32 v86, 0, v86
	v_max_f32_e32 v88, 0, v88
	v_max_f32_e32 v87, 0, v87
	v_max_f32_e32 v89, 0, v89
	v_pk_mul_f32 v[90:91], v[84:85], v[84:85]
	v_pk_mul_f32 v[86:87], v[86:87], v[86:87]
	v_pk_mul_f32 v[92:93], v[92:93], v[92:93]
	v_pk_mul_f32 v[88:89], v[88:89], v[88:89]

; __device__ __forceinline__ unsigned cvt_pk_bf16(float lo, float hi) { unsigned r; asm volatile("v_cvt_pk_bf16_f32 %0, %1, %2" : "=v"(r) : "v"(lo), "v"(hi)); return r; }
;     __device__ __forceinline__ void operator()(const f32x4 (&acc)[2][2][4][2], const Unit& u, int wr, int wc, int fr, int fq) const {
;     ...
;                 const float rs = __builtin_amdgcn_rsqf((float)ss[r] * (1.0f / 1048576.0f) * (1.0f / 1024.0f) + EPS);
;                 bf16_t* rowp = O + (size_t)r * ldc + colt + wc * 32 + 8 * fq;
; #pragma unroll
;                 for (int bj = 0; bj < 2; ++bj) { f32x4 v0 = acc[ai][bj][m][0] * rs, v1 = acc[ai][bj][m][1] * rs;
;                     if (mode == 2) {
; #pragma unroll
;                         for (int e = 0; e < 4; ++e) { float a = fmaxf(v0[e], 0.f), b = fmaxf(v1[e], 0.f); v0[e] = a * a; v1[e] = b * b; } }
;                     if (mode == 1 && colt >= 2048) {
; #pragma unroll
;                         for (int e = 0; e < 4; ++e) { v0[e] = __builtin_amdgcn_rcpf(1.0f + __builtin_amdgcn_exp2f(-1.4426950408889634f * v0[e])); v1[e] = __builtin_amdgcn_rcpf(1.0f + __builtin_amdgcn_exp2f(-1.4426950408889634f * v1[e])); } }
;                     u32x4 w; w.x = cvt_pk_bf16(v0[0], v0[1]); w.y = cvt_pk_bf16(v0[2], v0[3]); w.z = cvt_pk_bf16(v1[0], v1[1]); w.w = cvt_pk_bf16(v1[2], v1[3]);
;                     *(u32x4*)(rowp + bj * HALF) = w; }
.LBB0_408:
	v_cvt_pk_bf16_f32 v90, v90, v91
	v_cvt_pk_bf16_f32 v91, v86, v87
	v_cvt_pk_bf16_f32 v92, v82, v83
	v_cvt_pk_bf16_f32 v93, v88, v89
	global_store_dwordx4 v[208:209], v[90:93], off offset:256
	v_lshl_add_u64 v[208:209], v[208:209], 0, v[210:211]
	s_and_b64 vcc, exec, s[42:43]
	s_nop 1
	v_mov_b32_e32 v82, v248
	s_nop 0
	v_pk_mul_f32 v[86:87], v[30:31], v[82:83] op_sel_hi:[1,0]
	v_pk_mul_f32 v[90:91], v[28:29], v[82:83] op_sel_hi:[1,0]
	v_pk_mul_f32 v[88:89], v[26:27], v[82:83] op_sel_hi:[1,0]
	v_pk_mul_f32 v[92:93], v[24:25], v[82:83] op_sel_hi:[1,0]
	s_cbranch_vccnz .LBB0_410
	v_max_f32_e32 v84, 0, v90
	v_max_f32_e32 v92, 0, v92
	v_max_f32_e32 v85, 0, v91
	v_max_f32_e32 v93, 0, v93
	v_max_f32_e32 v86, 0, v86
	v_max_f32_e32 v88, 0, v88
	v_max_f32_e32 v87, 0, v87
	v_max_f32_e32 v89, 0, v89
	v_pk_mul_f32 v[90:91], v[84:85], v[84:85]
	v_pk_mul_f32 v[86:87], v[86:87], v[86:87]
	v_pk_mul_f32 v[92:93], v[92:93], v[92:93]
	v_pk_mul_f32 v[88:89], v[88:89], v[88:89]

; __device__ __forceinline__ unsigned cvt_pk_bf16(float lo, float hi) { unsigned r; asm volatile("v_cvt_pk_bf16_f32 %0, %1, %2" : "=v"(r) : "v"(lo), "v"(hi)); return r; }
;     __device__ __forceinline__ void operator()(const f32x4 (&acc)[2][2][4][2], const Unit& u, int wr, int wc, int fr, int fq) const {
;     ...
;                 const float rs = __builtin_amdgcn_rsqf((float)ss[r] * (1.0f / 1048576.0f) * (1.0f / 1024.0f) + EPS);
;                 bf16_t* rowp = O + (size_t)r * ldc + colt + wc * 32 + 8 * fq;
; #pragma unroll
;                 for (int bj = 0; bj < 2; ++bj) { f32x4 v0 = acc[ai][bj][m][0] * rs, v1 = acc[ai][bj][m][1] * rs;
;                     if (mode == 2) {
; #pragma unroll
;                         for (int e = 0; e < 4; ++e) { float a = fmaxf(v0[e], 0.f), b = fmaxf(v1[e], 0.f); v0[e] = a * a; v1[e] = b * b; } }
;                     if (mode == 1 && colt >= 2048) {
; #pragma unroll
;                         for (int e = 0; e < 4; ++e) { v0[e] = __builtin_amdgcn_rcpf(1.0f + __builtin_amdgcn_exp2f(-1.4426950408889634f * v0[e])); v1[e] = __builtin_amdgcn_rcpf(1.0f + __builtin_amdgcn_exp2f(-1.4426950408889634f * v1[e])); } }
;                     u32x4 w; w.x = cvt_pk_bf16(v0[0], v0[1]); w.y = cvt_pk_bf16(v0[2], v0[3]); w.z = cvt_pk_bf16(v1[0], v1[1]); w.w = cvt_pk_bf16(v1[2], v1[3]);
;                     *(u32x4*)(rowp + bj * HALF) = w; }
.LBB0_416:
	v_cvt_pk_bf16_f32 v90, v90, v91
	v_cvt_pk_bf16_f32 v91, v86, v87
	v_cvt_pk_bf16_f32 v92, v82, v83
	v_cvt_pk_bf16_f32 v93, v88, v89
	global_store_dwordx4 v[208:209], v[90:93], off offset:256
	v_lshl_add_u64 v[208:209], v[208:209], 0, v[210:211]
	s_and_b64 vcc, exec, s[42:43]
	s_nop 1
	v_mov_b32_e32 v80, v249
	s_nop 0
	v_pk_mul_f32 v[84:85], v[14:15], v[80:81] op_sel_hi:[1,0]
	v_pk_mul_f32 v[88:89], v[12:13], v[80:81] op_sel_hi:[1,0]
	v_pk_mul_f32 v[86:87], v[10:11], v[80:81] op_sel_hi:[1,0]
	v_pk_mul_f32 v[90:91], v[8:9], v[80:81] op_sel_hi:[1,0]
	s_cbranch_vccnz .LBB0_418
	v_max_f32_e32 v82, 0, v88
	v_max_f32_e32 v90, 0, v90
	v_max_f32_e32 v83, 0, v89
	v_max_f32_e32 v91, 0, v91
	v_max_f32_e32 v84, 0, v84
	v_max_f32_e32 v86, 0, v86
	v_max_f32_e32 v85, 0, v85
	v_max_f32_e32 v87, 0, v87
	v_pk_mul_f32 v[88:89], v[82:83], v[82:83]
	v_pk_mul_f32 v[84:85], v[84:85], v[84:85]
	v_pk_mul_f32 v[90:91], v[90:91], v[90:91]
	v_pk_mul_f32 v[86:87], v[86:87], v[86:87]

; DI float x16_sum(float x) { const unsigned u = __builtin_bit_cast(unsigned, x); auto r = __builtin_amdgcn_permlane16_swap(u, u, false, false); return __builtin_bit_cast(float, (unsigned)r[0]) + __builtin_bit_cast(float, (unsigned)r[1]); }
; DI float x32_sum(float x) { const unsigned u = __builtin_bit_cast(unsigned, x); auto r = __builtin_amdgcn_permlane32_swap(u, u, false, false); return __builtin_bit_cast(float, (unsigned)r[0]) + __builtin_bit_cast(float, (unsigned)r[1]); }
;     __device__ __forceinline__ void operator()(const f32x4 (&acc)[2][2][4][2], const Unit& u, int wr, int wc, int fr, int fq) const {
;     ...
;             const int blk = colt >> 10, g = blk % 3, sec = blk / 3; const int dsh = (g == 0) ? 0 : (g == 1 ? 2 : 4); const int cin = (colt & 1023) + 64 * wc + 8 * fq;
;             f32x4 gn[2][2];
;             const float* gp = (sec == 0) ? qg + g * 64 : kg + g * 64;
; #pragma unroll
;             for (int bj = 0; bj < 2; ++bj)
; #pragma unroll
;                 for (int n = 0; n < 2; ++n) gn[bj][n] = (sec < 2) ? *(const f32x4*)(gp + 32 * bj + 8 * fq + 4 * n) : (f32x4){1.f, 1.f, 1.f, 1.f};
;             const float qsc = (sec == 0) ? 0.125f * 1.4426950408889634f : 1.0f;
; #pragma unroll
;             for (int ai = 0; ai < 2; ++ai)
; #pragma unroll
;                 for (int m = 0; m < 4; ++m) {
;                     const int r = row0 + ai * HALF + m * 16;
;                     const float rs = __builtin_amdgcn_rsqf((float)ss[r] * (1.0f / 1048576.0f) * (1.0f / 1024.0f) + EPS);
;                     f32x4 v[2][2]; float sq = 0.f;
; #pragma unroll
;                     for (int bj = 0; bj < 2; ++bj)
; #pragma unroll
;                         for (int n = 0; n < 2; ++n) { v[bj][n] = acc[ai][bj][m][n] * rs; sq += (v[bj][n][0] * v[bj][n][0] + v[bj][n][1] * v[bj][n][1]) + (v[bj][n][2] * v[bj][n][2] + v[bj][n][3] * v[bj][n][3]); }
;                     sq = x16_sum(sq); sq = x32_sum(sq);
;                     const float r2 = (sec < 2) ? qsc * __builtin_amdgcn_rsqf(sq * (1.0f / 64.0f) + EPS) : 1.0f;
;                     const int bl = r >> 13, t = r & 8191; const int pr = (bl << 13) + ((t & ((1 << dsh) - 1)) << (13 - dsh)) + (t >> dsh);
.LBB0_433:
	s_cmp_ge_u32 s88, 6
	s_cbranch_scc1 .Lv433
	s_mov_b32 vcc_lo, 0xff00ff00
	s_mov_b32 vcc_hi, 0xff00ff00
	s_nop 1
	v_lshl_add_u64 v[162:163], v[160:161], 3, s[48:49]
	s_cmp_eq_u32 s2, 1
	s_cselect_b32 s34, 2, 4
	s_cmp_lg_u32 s2, 0
	v_cndmask_b32_e64 v171, 1.0, v234, s[0:1]
	s_cselect_b32 s34, s34, 0
	s_sub_i32 s42, 13, s34
	s_and_b32 s43, s69, 0xffffe000
	s_ashr_i32 s89, s88, 31
	s_and_b32 s2, s76, 0x300
	s_lshl_b64 s[0:1], s[88:89], 25
	s_add_u32 s0, s28, s0
	v_or_b32_e32 v172, s2, v169
	s_addc_u32 s1, s29, s1
	s_movk_i32 s2, 0x1fdf
	s_mov_b32 s88, 0x1000
	s_cmp_eq_u32 s34, 0
	s_cselect_b32 s88, 0x4000, s88
	s_cmp_eq_u32 s34, 4
	s_cselect_b32 s88, 0x800000, s88
	s_lshr_b32 s89, 0x8000, s34
	v_mov_b32_e32 v220, s88
	v_mov_b32_e32 v176, s89
	s_mul_i32 s89, s89, 5
	v_mov_b32_e32 v177, 0
	v_sub_u32_e32 v218, 64, v220
	v_mov_b32_e32 v178, s89
	v_mov_b32_e32 v179, 0
	v_cndmask_b32_e64 v219, 0, -1, vcc
	v_cndmask_b32_e64 v218, 0, v218, vcc
	v_cndmask_b32_e64 v220, v220, 64, vcc
	v_mov_b32_e32 v221, 0
	s_waitcnt vmcnt(0)
	v_readlane_b32 s88, v250, 51
	s_nop 1
	s_cmp_eq_u32 s88, 0
	s_cbranch_scc1 .Lss_nc_b
	v_cvt_f32_u32_e32 v223, v193
	v_cvt_f32_u32_e32 v222, v192
	v_fmamk_f32 v222, v223, 0x4f800000, v222
	v_fmamk_f32 v222, v222, 0x30800000, v229
	v_rsq_f32_e32 v242, v222
	v_cvt_f32_u32_e32 v223, v195
	v_cvt_f32_u32_e32 v222, v194
	v_fmamk_f32 v222, v223, 0x4f800000, v222
	v_fmamk_f32 v222, v222, 0x30800000, v229
	v_rsq_f32_e32 v243, v222
	v_cvt_f32_u32_e32 v223, v197
	v_cvt_f32_u32_e32 v222, v196
	v_fmamk_f32 v222, v223, 0x4f800000, v222
	v_fmamk_f32 v222, v222, 0x30800000, v229
	v_rsq_f32_e32 v244, v222
	v_cvt_f32_u32_e32 v223, v199
	v_cvt_f32_u32_e32 v222, v198
	v_fmamk_f32 v222, v223, 0x4f800000, v222
	v_fmamk_f32 v222, v222, 0x30800000, v229
	v_rsq_f32_e32 v245, v222
	v_cvt_f32_u32_e32 v223, v201
	v_cvt_f32_u32_e32 v222, v200
	v_fmamk_f32 v222, v223, 0x4f800000, v222
	v_fmamk_f32 v222, v222, 0x30800000, v229
	v_rsq_f32_e32 v246, v222
	v_cvt_f32_u32_e32 v223, v203
	v_cvt_f32_u32_e32 v222, v202
	v_fmamk_f32 v222, v223, 0x4f800000, v222
	v_fmamk_f32 v222, v222, 0x30800000, v229
	v_rsq_f32_e32 v247, v222
	v_cvt_f32_u32_e32 v223, v205
	v_cvt_f32_u32_e32 v222, v204
	v_fmamk_f32 v222, v223, 0x4f800000, v222
	v_fmamk_f32 v222, v222, 0x30800000, v229
	v_rsq_f32_e32 v248, v222
	v_cvt_f32_u32_e32 v223, v207
	v_cvt_f32_u32_e32 v222, v206
	v_fmamk_f32 v222, v223, 0x4f800000, v222
	v_fmamk_f32 v222, v222, 0x30800000, v229
	v_rsq_f32_e32 v249, v222
	v_writelane_b32 v250, 0, 51
.Lss_nc_b:
	s_nop 1
	v_mov_b32_e32 v112, v242
	s_nop 0
	v_pk_mul_f32 v[144:145], v[144:145], v[112:113] op_sel_hi:[1,0]
	v_pk_mul_f32 v[222:223], v[144:145], v[144:145]
	v_pk_mul_f32 v[164:165], v[142:143], v[112:113] op_sel_hi:[1,0]
	v_pk_fma_f32 v[222:223], v[164:165], v[164:165], v[222:223]
	v_pk_mul_f32 v[140:141], v[140:141], v[112:113] op_sel_hi:[1,0]
	v_pk_fma_f32 v[222:223], v[140:141], v[140:141], v[222:223]
	v_pk_mul_f32 v[142:143], v[138:139], v[112:113] op_sel_hi:[1,0]
	v_pk_fma_f32 v[222:223], v[142:143], v[142:143], v[222:223]
	v_pk_mul_f32 v[136:137], v[136:137], v[112:113] op_sel_hi:[1,0]
	v_pk_fma_f32 v[222:223], v[136:137], v[136:137], v[222:223]
	v_pk_mul_f32 v[138:139], v[134:135], v[112:113] op_sel_hi:[1,0]
	v_pk_fma_f32 v[222:223], v[138:139], v[138:139], v[222:223]
	v_pk_mul_f32 v[132:133], v[132:133], v[112:113] op_sel_hi:[1,0]
	v_pk_fma_f32 v[222:223], v[132:133], v[132:133], v[222:223]
	v_pk_mul_f32 v[134:135], v[130:131], v[112:113] op_sel_hi:[1,0]
	v_pk_fma_f32 v[222:223], v[134:135], v[134:135], v[222:223]
	v_add_f32_e32 v112, v222, v223
	v_mov_b32_e32 v130, v112
	s_nop 1
	v_permlane16_swap_b32_e32 v112, v130
	v_add_f32_e32 v112, v112, v130
	v_mov_b32_e32 v130, v112
	s_nop 1
	v_permlane32_swap_b32_e32 v112, v130
	v_add_f32_e32 v112, v112, v130
	v_fmamk_f32 v112, v112, 0x3c800000, v229
	v_rsq_f32_e32 v112, v112
	v_lshlrev_b32_e32 v131, s42, v160
	v_and_b32_e32 v131, 0x1ffe, v131
	v_pk_mul_f32 v[164:165], v[92:93], v[164:165]
	v_mul_f32_e32 v112, v171, v112
	v_cndmask_b32_e64 v130, 1.0, v112, s[40:41]
	v_and_b32_e32 v112, 0x1fcf, v160
	v_lshrrev_b32_e32 v112, s34, v112
	v_or_b32_e32 v112, s43, v112
	v_add_u32_e32 v166, v112, v131
	v_ashrrev_i32_e32 v167, 31, v166
	v_lshlrev_b64 v[166:167], 11, v[166:167]
	v_lshl_add_u64 v[166:167], s[0:1], 0, v[166:167]
	v_lshlrev_b32_e32 v112, 1, v172
	v_pk_mul_f32 v[144:145], v[94:95], v[144:145]
	v_pk_mul_f32 v[142:143], v[88:89], v[142:143]
	v_pk_mul_f32 v[140:141], v[90:91], v[140:141]
	v_lshl_add_u64 v[166:167], v[166:167], 0, v[112:113]
	v_pk_mul_f32 v[144:145], v[144:145], v[130:131] op_sel_hi:[1,0]
	v_pk_mul_f32 v[164:165], v[164:165], v[130:131] op_sel_hi:[1,0]
	v_pk_mul_f32 v[172:173], v[140:141], v[130:131] op_sel_hi:[1,0]
	v_pk_mul_f32 v[142:143], v[142:143], v[130:131] op_sel_hi:[1,0]
	v_cvt_pk_bf16_f32 v184, v164, v165
	v_cvt_pk_bf16_f32 v185, v144, v145
	v_pk_mul_f32 v[134:135], v[80:81], v[134:135]
	v_pk_mul_f32 v[132:133], v[82:83], v[132:133]
	v_cvt_pk_bf16_f32 v186, v142, v143
	v_cvt_pk_bf16_f32 v187, v172, v173
	v_pk_mul_f32 v[138:139], v[84:85], v[138:139]
	v_pk_mul_f32 v[136:137], v[86:87], v[136:137]
	v_pk_mul_f32 v[140:141], v[132:133], v[130:131] op_sel_hi:[1,0]
	v_pk_mul_f32 v[132:133], v[134:135], v[130:131] op_sel_hi:[1,0]
	v_pk_mul_f32 v[136:137], v[136:137], v[130:131] op_sel_hi:[1,0]
	v_pk_mul_f32 v[138:139], v[138:139], v[130:131] op_sel_hi:[1,0]
	s_nop 0
	v_cvt_pk_bf16_f32 v130, v138, v139
	v_cvt_pk_bf16_f32 v131, v136, v137
	v_cvt_pk_bf16_f32 v132, v132, v133
	v_cvt_pk_bf16_f32 v133, v140, v141
	v_mov_b32_dpp v180, v184 row_ror:8 row_mask:0xf bank_mask:0xf
; __device__ __forceinline__ unsigned cvt_pk_bf16(float lo, float hi) { unsigned r; asm volatile("v_cvt_pk_bf16_f32 %0, %1, %2" : "=v"(r) : "v"(lo), "v"(hi)); return r; }
; DI float x16_sum(float x) { const unsigned u = __builtin_bit_cast(unsigned, x); auto r = __builtin_amdgcn_permlane16_swap(u, u, false, false); return __builtin_bit_cast(float, (unsigned)r[0]) + __builtin_bit_cast(float, (unsigned)r[1]); }
; DI float x32_sum(float x) { const unsigned u = __builtin_bit_cast(unsigned, x); auto r = __builtin_amdgcn_permlane32_swap(u, u, false, false); return __builtin_bit_cast(float, (unsigned)r[0]) + __builtin_bit_cast(float, (unsigned)r[1]); }
;     __device__ __forceinline__ void operator()(const f32x4 (&acc)[2][2][4][2], const Unit& u, int wr, int wc, int fr, int fq) const {
;     ...
;                     const int r = row0 + ai * HALF + m * 16;
;                     const float rs = __builtin_amdgcn_rsqf((float)ss[r] * (1.0f / 1048576.0f) * (1.0f / 1024.0f) + EPS);
;                     f32x4 v[2][2]; float sq = 0.f;
; #pragma unroll
;                     for (int bj = 0; bj < 2; ++bj)
; #pragma unroll
;                         for (int n = 0; n < 2; ++n) { v[bj][n] = acc[ai][bj][m][n] * rs; sq += (v[bj][n][0] * v[bj][n][0] + v[bj][n][1] * v[bj][n][1]) + (v[bj][n][2] * v[bj][n][2] + v[bj][n][3] * v[bj][n][3]); }
;                     sq = x16_sum(sq); sq = x32_sum(sq);
;                     const float r2 = (sec < 2) ? qsc * __builtin_amdgcn_rsqf(sq * (1.0f / 64.0f) + EPS) : 1.0f;
;                     const int bl = r >> 13, t = r & 8191; const int pr = (bl << 13) + ((t & ((1 << dsh) - 1)) << (13 - dsh)) + (t >> dsh);
;                     bf16_t* rowp = O + (size_t)blk * SEC + (size_t)pr * 1024 + cin;
; #pragma unroll
;                     for (int bj = 0; bj < 2; ++bj) { const f32x4 v0 = v[bj][0] * gn[bj][0] * r2, v1 = v[bj][1] * gn[bj][1] * r2;
;                         u32x4 w; w.x = cvt_pk_bf16(v0[0], v0[1]); w.y = cvt_pk_bf16(v0[2], v0[3]); w.z = cvt_pk_bf16(v1[0], v1[1]); w.w = cvt_pk_bf16(v1[2], v1[3]);
;                         *(u32x4*)(rowp + bj * 32) = w; }
	v_mov_b32_dpp v181, v185 row_ror:8 row_mask:0xf bank_mask:0xf
	v_mov_b32_dpp v182, v186 row_ror:8 row_mask:0xf bank_mask:0xf
	v_mov_b32_dpp v183, v187 row_ror:8 row_mask:0xf bank_mask:0xf
	v_lshl_add_u64 v[212:213], v[166:167], 0, v[218:219]
	v_mov_b32_dpp v184, v130 row_ror:8 row_mask:0xf bank_mask:0xc
	v_mov_b32_dpp v185, v131 row_ror:8 row_mask:0xf bank_mask:0xc
	v_mov_b32_dpp v186, v132 row_ror:8 row_mask:0xf bank_mask:0xc
	v_mov_b32_dpp v187, v133 row_ror:8 row_mask:0xf bank_mask:0xc
	v_lshl_add_u64 v[214:215], v[166:167], 0, v[220:221]
	v_cndmask_b32_e32 v130, v180, v130, vcc
	v_cndmask_b32_e32 v131, v181, v131, vcc
	v_cndmask_b32_e32 v132, v182, v132, vcc
	v_cndmask_b32_e32 v133, v183, v133, vcc
	s_nop 0
	global_store_dwordx4 v[212:213], v[184:187], off
	global_store_dwordx4 v[214:215], v[130:133], off
	v_lshl_add_u64 v[174:175], v[166:167], 0, v[176:177]
	s_nop 1
	v_or_b32_e32 v133, 16, v160
	v_mov_b32_e32 v132, v243
	s_nop 0
	v_pk_mul_f32 v[128:129], v[128:129], v[132:133] op_sel_hi:[1,0]
	v_pk_mul_f32 v[222:223], v[128:129], v[128:129]
	v_pk_mul_f32 v[130:131], v[126:127], v[132:133] op_sel_hi:[1,0]
	v_pk_fma_f32 v[222:223], v[130:131], v[130:131], v[222:223]
	v_pk_mul_f32 v[124:125], v[124:125], v[132:133] op_sel_hi:[1,0]
	v_pk_fma_f32 v[222:223], v[124:125], v[124:125], v[222:223]
	v_pk_mul_f32 v[126:127], v[122:123], v[132:133] op_sel_hi:[1,0]
	v_pk_fma_f32 v[222:223], v[126:127], v[126:127], v[222:223]
	v_pk_mul_f32 v[120:121], v[120:121], v[132:133] op_sel_hi:[1,0]
	v_pk_fma_f32 v[222:223], v[120:121], v[120:121], v[222:223]
	v_pk_mul_f32 v[122:123], v[118:119], v[132:133] op_sel_hi:[1,0]
	v_pk_fma_f32 v[222:223], v[122:123], v[122:123], v[222:223]
	v_pk_mul_f32 v[116:117], v[116:117], v[132:133] op_sel_hi:[1,0]
	v_pk_fma_f32 v[222:223], v[116:117], v[116:117], v[222:223]
	v_pk_mul_f32 v[118:119], v[114:115], v[132:133] op_sel_hi:[1,0]
	v_pk_fma_f32 v[222:223], v[118:119], v[118:119], v[222:223]
	v_add_f32_e32 v114, v222, v223
	v_mov_b32_e32 v115, v114
	s_nop 1
	v_permlane16_swap_b32_e32 v114, v115
	v_add_f32_e32 v114, v114, v115
	v_mov_b32_e32 v115, v114
	s_nop 1
	v_permlane32_swap_b32_e32 v114, v115
	v_add_f32_e32 v114, v114, v115
	v_fmamk_f32 v114, v114, 0x3c800000, v229
	v_rsq_f32_e32 v114, v114
	s_nop 0
	v_mul_f32_e32 v114, v171, v114
	v_cndmask_b32_e64 v114, 1.0, v114, s[40:41]
	v_pk_mul_f32 v[130:131], v[92:93], v[130:131]
	v_pk_mul_f32 v[128:129], v[94:95], v[128:129]
	v_pk_mul_f32 v[126:127], v[88:89], v[126:127]
	v_pk_mul_f32 v[124:125], v[90:91], v[124:125]
	v_pk_mul_f32 v[128:129], v[128:129], v[114:115] op_sel_hi:[1,0]
	v_pk_mul_f32 v[130:131], v[130:131], v[114:115] op_sel_hi:[1,0]
	v_pk_mul_f32 v[134:135], v[124:125], v[114:115] op_sel_hi:[1,0]
	v_pk_mul_f32 v[126:127], v[126:127], v[114:115] op_sel_hi:[1,0]
	v_cvt_pk_bf16_f32 v184, v130, v131
	v_cvt_pk_bf16_f32 v185, v128, v129
	v_pk_mul_f32 v[118:119], v[80:81], v[118:119]
	v_pk_mul_f32 v[116:117], v[82:83], v[116:117]
	v_cvt_pk_bf16_f32 v186, v126, v127
	v_cvt_pk_bf16_f32 v187, v134, v135
	v_pk_mul_f32 v[122:123], v[84:85], v[122:123]
	v_pk_mul_f32 v[120:121], v[86:87], v[120:121]
	v_pk_mul_f32 v[124:125], v[116:117], v[114:115] op_sel_hi:[1,0]
	v_pk_mul_f32 v[116:117], v[118:119], v[114:115] op_sel_hi:[1,0]
	v_pk_mul_f32 v[120:121], v[120:121], v[114:115] op_sel_hi:[1,0]
	v_pk_mul_f32 v[122:123], v[122:123], v[114:115] op_sel_hi:[1,0]
	s_movk_i32 s2, 0x1fef
	v_cvt_pk_bf16_f32 v114, v122, v123
	v_cvt_pk_bf16_f32 v115, v120, v121
	v_cvt_pk_bf16_f32 v116, v116, v117
	v_cvt_pk_bf16_f32 v117, v124, v125
	v_mov_b32_dpp v180, v184 row_ror:8 row_mask:0xf bank_mask:0xf
	v_mov_b32_dpp v181, v185 row_ror:8 row_mask:0xf bank_mask:0xf
	v_mov_b32_dpp v182, v186 row_ror:8 row_mask:0xf bank_mask:0xf
	v_mov_b32_dpp v183, v187 row_ror:8 row_mask:0xf bank_mask:0xf
	v_lshl_add_u64 v[212:213], v[174:175], 0, v[218:219]
	v_mov_b32_dpp v184, v114 row_ror:8 row_mask:0xf bank_mask:0xc
	v_mov_b32_dpp v185, v115 row_ror:8 row_mask:0xf bank_mask:0xc
	v_mov_b32_dpp v186, v116 row_ror:8 row_mask:0xf bank_mask:0xc
	v_mov_b32_dpp v187, v117 row_ror:8 row_mask:0xf bank_mask:0xc
	v_lshl_add_u64 v[214:215], v[174:175], 0, v[220:221]
	v_cndmask_b32_e32 v114, v180, v114, vcc
	v_cndmask_b32_e32 v115, v181, v115, vcc
	v_cndmask_b32_e32 v116, v182, v116, vcc
	v_cndmask_b32_e32 v117, v183, v117, vcc
	s_nop 0
	global_store_dwordx4 v[212:213], v[184:187], off
	global_store_dwordx4 v[214:215], v[114:117], off
	v_lshl_add_u64 v[174:175], v[174:175], 0, v[176:177]
	s_nop 1
	v_or_b32_e32 v117, 32, v160
	v_mov_b32_e32 v116, v244
	s_nop 0
	v_pk_mul_f32 v[110:111], v[110:111], v[116:117] op_sel_hi:[1,0]
	v_pk_mul_f32 v[222:223], v[110:111], v[110:111]
	v_pk_mul_f32 v[114:115], v[108:109], v[116:117] op_sel_hi:[1,0]
	v_pk_fma_f32 v[222:223], v[114:115], v[114:115], v[222:223]
	v_pk_mul_f32 v[106:107], v[106:107], v[116:117] op_sel_hi:[1,0]
	v_pk_fma_f32 v[222:223], v[106:107], v[106:107], v[222:223]
	v_pk_mul_f32 v[108:109], v[104:105], v[116:117] op_sel_hi:[1,0]
	v_pk_fma_f32 v[222:223], v[108:109], v[108:109], v[222:223]
	v_pk_mul_f32 v[102:103], v[102:103], v[116:117] op_sel_hi:[1,0]
	v_pk_fma_f32 v[222:223], v[102:103], v[102:103], v[222:223]
	v_pk_mul_f32 v[104:105], v[100:101], v[116:117] op_sel_hi:[1,0]
	v_pk_fma_f32 v[222:223], v[104:105], v[104:105], v[222:223]
	v_pk_mul_f32 v[98:99], v[98:99], v[116:117] op_sel_hi:[1,0]
	v_pk_fma_f32 v[222:223], v[98:99], v[98:99], v[222:223]
	v_pk_mul_f32 v[100:101], v[96:97], v[116:117] op_sel_hi:[1,0]
	v_pk_fma_f32 v[222:223], v[100:101], v[100:101], v[222:223]
	v_add_f32_e32 v96, v222, v223
	v_mov_b32_e32 v97, v96
	s_nop 1
	v_permlane16_swap_b32_e32 v96, v97
; __device__ __forceinline__ unsigned cvt_pk_bf16(float lo, float hi) { unsigned r; asm volatile("v_cvt_pk_bf16_f32 %0, %1, %2" : "=v"(r) : "v"(lo), "v"(hi)); return r; }
; DI float x16_sum(float x) { const unsigned u = __builtin_bit_cast(unsigned, x); auto r = __builtin_amdgcn_permlane16_swap(u, u, false, false); return __builtin_bit_cast(float, (unsigned)r[0]) + __builtin_bit_cast(float, (unsigned)r[1]); }
; DI float x32_sum(float x) { const unsigned u = __builtin_bit_cast(unsigned, x); auto r = __builtin_amdgcn_permlane32_swap(u, u, false, false); return __builtin_bit_cast(float, (unsigned)r[0]) + __builtin_bit_cast(float, (unsigned)r[1]); }
;     __device__ __forceinline__ void operator()(const f32x4 (&acc)[2][2][4][2], const Unit& u, int wr, int wc, int fr, int fq) const {
;     ...
;                     const int r = row0 + ai * HALF + m * 16;
;                     const float rs = __builtin_amdgcn_rsqf((float)ss[r] * (1.0f / 1048576.0f) * (1.0f / 1024.0f) + EPS);
;                     f32x4 v[2][2]; float sq = 0.f;
; #pragma unroll
;                     for (int bj = 0; bj < 2; ++bj)
; #pragma unroll
;                         for (int n = 0; n < 2; ++n) { v[bj][n] = acc[ai][bj][m][n] * rs; sq += (v[bj][n][0] * v[bj][n][0] + v[bj][n][1] * v[bj][n][1]) + (v[bj][n][2] * v[bj][n][2] + v[bj][n][3] * v[bj][n][3]); }
;                     sq = x16_sum(sq); sq = x32_sum(sq);
;                     const float r2 = (sec < 2) ? qsc * __builtin_amdgcn_rsqf(sq * (1.0f / 64.0f) + EPS) : 1.0f;
;                     const int bl = r >> 13, t = r & 8191; const int pr = (bl << 13) + ((t & ((1 << dsh) - 1)) << (13 - dsh)) + (t >> dsh);
;                     bf16_t* rowp = O + (size_t)blk * SEC + (size_t)pr * 1024 + cin;
; #pragma unroll
;                     for (int bj = 0; bj < 2; ++bj) { const f32x4 v0 = v[bj][0] * gn[bj][0] * r2, v1 = v[bj][1] * gn[bj][1] * r2;
;                         u32x4 w; w.x = cvt_pk_bf16(v0[0], v0[1]); w.y = cvt_pk_bf16(v0[2], v0[3]); w.z = cvt_pk_bf16(v1[0], v1[1]); w.w = cvt_pk_bf16(v1[2], v1[3]);
;                         *(u32x4*)(rowp + bj * 32) = w; }
	v_add_f32_e32 v96, v96, v97
	v_mov_b32_e32 v97, v96
	s_nop 1
	v_permlane32_swap_b32_e32 v96, v97
	v_add_f32_e32 v96, v96, v97
	v_fmamk_f32 v96, v96, 0x3c800000, v229
	v_rsq_f32_e32 v96, v96
	s_nop 0
	v_mul_f32_e32 v96, v171, v96
	v_cndmask_b32_e64 v96, 1.0, v96, s[40:41]
	v_pk_mul_f32 v[114:115], v[92:93], v[114:115]
	v_pk_mul_f32 v[110:111], v[94:95], v[110:111]
	v_pk_mul_f32 v[108:109], v[88:89], v[108:109]
	v_pk_mul_f32 v[106:107], v[90:91], v[106:107]
	v_pk_mul_f32 v[110:111], v[110:111], v[96:97] op_sel_hi:[1,0]
	v_pk_mul_f32 v[114:115], v[114:115], v[96:97] op_sel_hi:[1,0]
	v_pk_mul_f32 v[118:119], v[106:107], v[96:97] op_sel_hi:[1,0]
	v_pk_mul_f32 v[108:109], v[108:109], v[96:97] op_sel_hi:[1,0]
	v_cvt_pk_bf16_f32 v184, v114, v115
	v_cvt_pk_bf16_f32 v185, v110, v111
	v_pk_mul_f32 v[100:101], v[80:81], v[100:101]
	v_pk_mul_f32 v[98:99], v[82:83], v[98:99]
	v_cvt_pk_bf16_f32 v186, v108, v109
	v_cvt_pk_bf16_f32 v187, v118, v119
	v_pk_mul_f32 v[104:105], v[84:85], v[104:105]
	v_pk_mul_f32 v[102:103], v[86:87], v[102:103]
	v_pk_mul_f32 v[106:107], v[98:99], v[96:97] op_sel_hi:[1,0]
	v_pk_mul_f32 v[98:99], v[100:101], v[96:97] op_sel_hi:[1,0]
	v_pk_mul_f32 v[102:103], v[102:103], v[96:97] op_sel_hi:[1,0]
	v_pk_mul_f32 v[104:105], v[104:105], v[96:97] op_sel_hi:[1,0]
	s_movk_i32 s2, 0x1fff
	v_cvt_pk_bf16_f32 v96, v104, v105
	v_cvt_pk_bf16_f32 v97, v102, v103
	v_cvt_pk_bf16_f32 v98, v98, v99
	v_cvt_pk_bf16_f32 v99, v106, v107
	v_mov_b32_dpp v180, v184 row_ror:8 row_mask:0xf bank_mask:0xf
	v_mov_b32_dpp v181, v185 row_ror:8 row_mask:0xf bank_mask:0xf
	v_mov_b32_dpp v182, v186 row_ror:8 row_mask:0xf bank_mask:0xf
	v_mov_b32_dpp v183, v187 row_ror:8 row_mask:0xf bank_mask:0xf
	v_lshl_add_u64 v[212:213], v[174:175], 0, v[218:219]
	v_mov_b32_dpp v184, v96 row_ror:8 row_mask:0xf bank_mask:0xc
	v_mov_b32_dpp v185, v97 row_ror:8 row_mask:0xf bank_mask:0xc
	v_mov_b32_dpp v186, v98 row_ror:8 row_mask:0xf bank_mask:0xc
	v_mov_b32_dpp v187, v99 row_ror:8 row_mask:0xf bank_mask:0xc
	v_lshl_add_u64 v[214:215], v[174:175], 0, v[220:221]
	v_cndmask_b32_e32 v96, v180, v96, vcc
	v_cndmask_b32_e32 v97, v181, v97, vcc
	v_cndmask_b32_e32 v98, v182, v98, vcc
	v_cndmask_b32_e32 v99, v183, v99, vcc
	s_nop 0
	global_store_dwordx4 v[212:213], v[184:187], off
	global_store_dwordx4 v[214:215], v[96:99], off
	v_lshl_add_u64 v[174:175], v[174:175], 0, v[176:177]
	s_nop 1
	v_or_b32_e32 v99, 48, v160
	v_mov_b32_e32 v98, v245
	s_nop 0
	v_pk_mul_f32 v[78:79], v[78:79], v[98:99] op_sel_hi:[1,0]
	v_pk_mul_f32 v[222:223], v[78:79], v[78:79]
	v_pk_mul_f32 v[96:97], v[76:77], v[98:99] op_sel_hi:[1,0]
	v_pk_fma_f32 v[222:223], v[96:97], v[96:97], v[222:223]
	v_pk_mul_f32 v[74:75], v[74:75], v[98:99] op_sel_hi:[1,0]
	v_pk_fma_f32 v[222:223], v[74:75], v[74:75], v[222:223]
	v_pk_mul_f32 v[76:77], v[72:73], v[98:99] op_sel_hi:[1,0]
	v_pk_fma_f32 v[222:223], v[76:77], v[76:77], v[222:223]
	v_pk_mul_f32 v[70:71], v[70:71], v[98:99] op_sel_hi:[1,0]
	v_pk_fma_f32 v[222:223], v[70:71], v[70:71], v[222:223]
	v_pk_mul_f32 v[72:73], v[68:69], v[98:99] op_sel_hi:[1,0]
	v_pk_fma_f32 v[222:223], v[72:73], v[72:73], v[222:223]
	v_pk_mul_f32 v[66:67], v[66:67], v[98:99] op_sel_hi:[1,0]
	v_pk_fma_f32 v[222:223], v[66:67], v[66:67], v[222:223]
	v_pk_mul_f32 v[68:69], v[64:65], v[98:99] op_sel_hi:[1,0]
	v_pk_fma_f32 v[222:223], v[68:69], v[68:69], v[222:223]
	v_add_f32_e32 v64, v222, v223
	v_mov_b32_e32 v65, v64
	s_nop 1
	v_permlane16_swap_b32_e32 v64, v65
	v_add_f32_e32 v64, v64, v65
	v_mov_b32_e32 v65, v64
	s_nop 1
	v_permlane32_swap_b32_e32 v64, v65
	v_add_f32_e32 v64, v64, v65
	v_fmamk_f32 v64, v64, 0x3c800000, v229
	v_rsq_f32_e32 v64, v64
	s_nop 0
	v_mul_f32_e32 v64, v171, v64
	v_cndmask_b32_e64 v64, 1.0, v64, s[40:41]
	v_pk_mul_f32 v[96:97], v[92:93], v[96:97]
	v_pk_mul_f32 v[78:79], v[94:95], v[78:79]
	v_pk_mul_f32 v[76:77], v[88:89], v[76:77]
	v_pk_mul_f32 v[74:75], v[90:91], v[74:75]
	v_pk_mul_f32 v[78:79], v[78:79], v[64:65] op_sel_hi:[1,0]
	v_pk_mul_f32 v[96:97], v[96:97], v[64:65] op_sel_hi:[1,0]
	v_pk_mul_f32 v[100:101], v[74:75], v[64:65] op_sel_hi:[1,0]
	v_pk_mul_f32 v[76:77], v[76:77], v[64:65] op_sel_hi:[1,0]
	v_cvt_pk_bf16_f32 v184, v96, v97
	v_cvt_pk_bf16_f32 v185, v78, v79
	v_pk_mul_f32 v[68:69], v[80:81], v[68:69]
	v_pk_mul_f32 v[66:67], v[82:83], v[66:67]
	v_cvt_pk_bf16_f32 v186, v76, v77
	v_cvt_pk_bf16_f32 v187, v100, v101
	v_pk_mul_f32 v[72:73], v[84:85], v[72:73]
	v_pk_mul_f32 v[70:71], v[86:87], v[70:71]
	v_pk_mul_f32 v[74:75], v[66:67], v[64:65] op_sel_hi:[1,0]
	v_pk_mul_f32 v[66:67], v[68:69], v[64:65] op_sel_hi:[1,0]
	v_pk_mul_f32 v[70:71], v[70:71], v[64:65] op_sel_hi:[1,0]
	v_pk_mul_f32 v[72:73], v[72:73], v[64:65] op_sel_hi:[1,0]
	s_nop 0
	v_cvt_pk_bf16_f32 v64, v72, v73
	v_cvt_pk_bf16_f32 v65, v70, v71
	v_cvt_pk_bf16_f32 v66, v66, v67
	v_cvt_pk_bf16_f32 v67, v74, v75
	v_mov_b32_dpp v180, v184 row_ror:8 row_mask:0xf bank_mask:0xf
	v_mov_b32_dpp v181, v185 row_ror:8 row_mask:0xf bank_mask:0xf
	v_mov_b32_dpp v182, v186 row_ror:8 row_mask:0xf bank_mask:0xf
	v_mov_b32_dpp v183, v187 row_ror:8 row_mask:0xf bank_mask:0xf
	v_lshl_add_u64 v[212:213], v[174:175], 0, v[218:219]
	v_mov_b32_dpp v184, v64 row_ror:8 row_mask:0xf bank_mask:0xc
	v_mov_b32_dpp v185, v65 row_ror:8 row_mask:0xf bank_mask:0xc
	v_mov_b32_dpp v186, v66 row_ror:8 row_mask:0xf bank_mask:0xc
	v_mov_b32_dpp v187, v67 row_ror:8 row_mask:0xf bank_mask:0xc
	v_lshl_add_u64 v[214:215], v[174:175], 0, v[220:221]
	v_cndmask_b32_e32 v64, v180, v64, vcc
	v_cndmask_b32_e32 v65, v181, v65, vcc
	v_cndmask_b32_e32 v66, v182, v66, vcc
	v_cndmask_b32_e32 v67, v183, v67, vcc
	s_nop 0
	global_store_dwordx4 v[212:213], v[184:187], off
; __device__ __forceinline__ unsigned cvt_pk_bf16(float lo, float hi) { unsigned r; asm volatile("v_cvt_pk_bf16_f32 %0, %1, %2" : "=v"(r) : "v"(lo), "v"(hi)); return r; }
; DI float x16_sum(float x) { const unsigned u = __builtin_bit_cast(unsigned, x); auto r = __builtin_amdgcn_permlane16_swap(u, u, false, false); return __builtin_bit_cast(float, (unsigned)r[0]) + __builtin_bit_cast(float, (unsigned)r[1]); }
; DI float x32_sum(float x) { const unsigned u = __builtin_bit_cast(unsigned, x); auto r = __builtin_amdgcn_permlane32_swap(u, u, false, false); return __builtin_bit_cast(float, (unsigned)r[0]) + __builtin_bit_cast(float, (unsigned)r[1]); }
;     __device__ __forceinline__ void operator()(const f32x4 (&acc)[2][2][4][2], const Unit& u, int wr, int wc, int fr, int fq) const {
;     ...
;                     const int r = row0 + ai * HALF + m * 16;
;                     const float rs = __builtin_amdgcn_rsqf((float)ss[r] * (1.0f / 1048576.0f) * (1.0f / 1024.0f) + EPS);
;                     f32x4 v[2][2]; float sq = 0.f;
; #pragma unroll
;                     for (int bj = 0; bj < 2; ++bj)
; #pragma unroll
;                         for (int n = 0; n < 2; ++n) { v[bj][n] = acc[ai][bj][m][n] * rs; sq += (v[bj][n][0] * v[bj][n][0] + v[bj][n][1] * v[bj][n][1]) + (v[bj][n][2] * v[bj][n][2] + v[bj][n][3] * v[bj][n][3]); }
;                     sq = x16_sum(sq); sq = x32_sum(sq);
;                     const float r2 = (sec < 2) ? qsc * __builtin_amdgcn_rsqf(sq * (1.0f / 64.0f) + EPS) : 1.0f;
;                     const int bl = r >> 13, t = r & 8191; const int pr = (bl << 13) + ((t & ((1 << dsh) - 1)) << (13 - dsh)) + (t >> dsh);
;                     bf16_t* rowp = O + (size_t)blk * SEC + (size_t)pr * 1024 + cin;
; #pragma unroll
;                     for (int bj = 0; bj < 2; ++bj) { const f32x4 v0 = v[bj][0] * gn[bj][0] * r2, v1 = v[bj][1] * gn[bj][1] * r2;
;                         u32x4 w; w.x = cvt_pk_bf16(v0[0], v0[1]); w.y = cvt_pk_bf16(v0[2], v0[3]); w.z = cvt_pk_bf16(v1[0], v1[1]); w.w = cvt_pk_bf16(v1[2], v1[3]);
;                         *(u32x4*)(rowp + bj * 32) = w; }
	global_store_dwordx4 v[214:215], v[64:67], off
	v_lshl_add_u64 v[174:175], v[174:175], 0, v[178:179]
	s_nop 1
	v_add_u32_e32 v67, 0x80, v160
	v_mov_b32_e32 v66, v246
	s_nop 0
	v_pk_mul_f32 v[62:63], v[62:63], v[66:67] op_sel_hi:[1,0]
	v_pk_mul_f32 v[222:223], v[62:63], v[62:63]
	v_pk_mul_f32 v[64:65], v[60:61], v[66:67] op_sel_hi:[1,0]
	v_pk_fma_f32 v[222:223], v[64:65], v[64:65], v[222:223]
	v_pk_mul_f32 v[58:59], v[58:59], v[66:67] op_sel_hi:[1,0]
	v_pk_fma_f32 v[222:223], v[58:59], v[58:59], v[222:223]
	v_pk_mul_f32 v[60:61], v[56:57], v[66:67] op_sel_hi:[1,0]
	v_pk_fma_f32 v[222:223], v[60:61], v[60:61], v[222:223]
	v_pk_mul_f32 v[54:55], v[54:55], v[66:67] op_sel_hi:[1,0]
	v_pk_fma_f32 v[222:223], v[54:55], v[54:55], v[222:223]
	v_pk_mul_f32 v[56:57], v[52:53], v[66:67] op_sel_hi:[1,0]
	v_pk_fma_f32 v[222:223], v[56:57], v[56:57], v[222:223]
	v_pk_mul_f32 v[50:51], v[50:51], v[66:67] op_sel_hi:[1,0]
	v_pk_fma_f32 v[222:223], v[50:51], v[50:51], v[222:223]
	v_pk_mul_f32 v[52:53], v[48:49], v[66:67] op_sel_hi:[1,0]
	v_pk_fma_f32 v[222:223], v[52:53], v[52:53], v[222:223]
	v_add_f32_e32 v48, v222, v223
	v_mov_b32_e32 v49, v48
	s_nop 1
	v_permlane16_swap_b32_e32 v48, v49
	v_add_f32_e32 v48, v48, v49
	v_mov_b32_e32 v49, v48
	s_nop 1
	v_permlane32_swap_b32_e32 v48, v49
	v_add_f32_e32 v48, v48, v49
	v_fmamk_f32 v48, v48, 0x3c800000, v229
	v_rsq_f32_e32 v48, v48
	s_nop 0
	v_mul_f32_e32 v48, v171, v48
	v_cndmask_b32_e64 v48, 1.0, v48, s[40:41]
	v_pk_mul_f32 v[64:65], v[92:93], v[64:65]
	v_pk_mul_f32 v[62:63], v[94:95], v[62:63]
	v_pk_mul_f32 v[60:61], v[88:89], v[60:61]
	v_pk_mul_f32 v[58:59], v[90:91], v[58:59]
	v_pk_mul_f32 v[62:63], v[62:63], v[48:49] op_sel_hi:[1,0]
	v_pk_mul_f32 v[64:65], v[64:65], v[48:49] op_sel_hi:[1,0]
	v_pk_mul_f32 v[70:71], v[58:59], v[48:49] op_sel_hi:[1,0]
	v_pk_mul_f32 v[60:61], v[60:61], v[48:49] op_sel_hi:[1,0]
	v_cvt_pk_bf16_f32 v184, v64, v65
	v_cvt_pk_bf16_f32 v185, v62, v63
	v_pk_mul_f32 v[52:53], v[80:81], v[52:53]
	v_pk_mul_f32 v[50:51], v[82:83], v[50:51]
	v_cvt_pk_bf16_f32 v186, v60, v61
	v_cvt_pk_bf16_f32 v187, v70, v71
	v_pk_mul_f32 v[56:57], v[84:85], v[56:57]
	v_pk_mul_f32 v[54:55], v[86:87], v[54:55]
	v_pk_mul_f32 v[58:59], v[50:51], v[48:49] op_sel_hi:[1,0]
	v_pk_mul_f32 v[50:51], v[52:53], v[48:49] op_sel_hi:[1,0]
	v_pk_mul_f32 v[54:55], v[54:55], v[48:49] op_sel_hi:[1,0]
	v_pk_mul_f32 v[56:57], v[56:57], v[48:49] op_sel_hi:[1,0]
	s_nop 0
	v_cvt_pk_bf16_f32 v48, v56, v57
	v_cvt_pk_bf16_f32 v49, v54, v55
	v_cvt_pk_bf16_f32 v50, v50, v51
	v_cvt_pk_bf16_f32 v51, v58, v59
	v_mov_b32_dpp v180, v184 row_ror:8 row_mask:0xf bank_mask:0xf
	v_mov_b32_dpp v181, v185 row_ror:8 row_mask:0xf bank_mask:0xf
	v_mov_b32_dpp v182, v186 row_ror:8 row_mask:0xf bank_mask:0xf
	v_mov_b32_dpp v183, v187 row_ror:8 row_mask:0xf bank_mask:0xf
	v_lshl_add_u64 v[212:213], v[174:175], 0, v[218:219]
	v_mov_b32_dpp v184, v48 row_ror:8 row_mask:0xf bank_mask:0xc
	v_mov_b32_dpp v185, v49 row_ror:8 row_mask:0xf bank_mask:0xc
	v_mov_b32_dpp v186, v50 row_ror:8 row_mask:0xf bank_mask:0xc
	v_mov_b32_dpp v187, v51 row_ror:8 row_mask:0xf bank_mask:0xc
	v_lshl_add_u64 v[214:215], v[174:175], 0, v[220:221]
	v_cndmask_b32_e32 v48, v180, v48, vcc
	v_cndmask_b32_e32 v49, v181, v49, vcc
	v_cndmask_b32_e32 v50, v182, v50, vcc
	v_cndmask_b32_e32 v51, v183, v51, vcc
	s_nop 0
	global_store_dwordx4 v[212:213], v[184:187], off
	global_store_dwordx4 v[214:215], v[48:51], off
	v_lshl_add_u64 v[174:175], v[174:175], 0, v[176:177]
	s_nop 1
	v_add_u32_e32 v51, 0x90, v160
	v_mov_b32_e32 v50, v247
	s_nop 0
	v_pk_mul_f32 v[46:47], v[46:47], v[50:51] op_sel_hi:[1,0]
	v_pk_mul_f32 v[222:223], v[46:47], v[46:47]
	v_pk_mul_f32 v[48:49], v[44:45], v[50:51] op_sel_hi:[1,0]
	v_pk_fma_f32 v[222:223], v[48:49], v[48:49], v[222:223]
	v_pk_mul_f32 v[42:43], v[42:43], v[50:51] op_sel_hi:[1,0]
	v_pk_fma_f32 v[222:223], v[42:43], v[42:43], v[222:223]
	v_pk_mul_f32 v[44:45], v[40:41], v[50:51] op_sel_hi:[1,0]
	v_pk_fma_f32 v[222:223], v[44:45], v[44:45], v[222:223]
	v_pk_mul_f32 v[38:39], v[38:39], v[50:51] op_sel_hi:[1,0]
	v_pk_fma_f32 v[222:223], v[38:39], v[38:39], v[222:223]
	v_pk_mul_f32 v[40:41], v[36:37], v[50:51] op_sel_hi:[1,0]
	v_pk_fma_f32 v[222:223], v[40:41], v[40:41], v[222:223]
	v_pk_mul_f32 v[34:35], v[34:35], v[50:51] op_sel_hi:[1,0]
	v_pk_fma_f32 v[222:223], v[34:35], v[34:35], v[222:223]
	v_pk_mul_f32 v[36:37], v[32:33], v[50:51] op_sel_hi:[1,0]
	v_pk_fma_f32 v[222:223], v[36:37], v[36:37], v[222:223]
	v_add_f32_e32 v32, v222, v223
	v_mov_b32_e32 v33, v32
	s_nop 1
	v_permlane16_swap_b32_e32 v32, v33
	v_add_f32_e32 v32, v32, v33
	v_mov_b32_e32 v33, v32
	s_nop 1
	v_permlane32_swap_b32_e32 v32, v33
	v_add_f32_e32 v32, v32, v33
	v_fmamk_f32 v32, v32, 0x3c800000, v229
	v_rsq_f32_e32 v32, v32
	s_nop 0
	v_mul_f32_e32 v32, v171, v32
	v_cndmask_b32_e64 v32, 1.0, v32, s[40:41]
	v_pk_mul_f32 v[48:49], v[92:93], v[48:49]
	v_pk_mul_f32 v[46:47], v[94:95], v[46:47]
	v_pk_mul_f32 v[44:45], v[88:89], v[44:45]
	v_pk_mul_f32 v[42:43], v[90:91], v[42:43]
	v_pk_mul_f32 v[46:47], v[46:47], v[32:33] op_sel_hi:[1,0]
	v_pk_mul_f32 v[48:49], v[48:49], v[32:33] op_sel_hi:[1,0]
	v_pk_mul_f32 v[52:53], v[42:43], v[32:33] op_sel_hi:[1,0]
	v_pk_mul_f32 v[44:45], v[44:45], v[32:33] op_sel_hi:[1,0]
	v_cvt_pk_bf16_f32 v184, v48, v49
	v_cvt_pk_bf16_f32 v185, v46, v47
	v_pk_mul_f32 v[36:37], v[80:81], v[36:37]
	v_pk_mul_f32 v[34:35], v[82:83], v[34:35]
	v_cvt_pk_bf16_f32 v186, v44, v45
	v_cvt_pk_bf16_f32 v187, v52, v53
	v_pk_mul_f32 v[40:41], v[84:85], v[40:41]
	v_pk_mul_f32 v[38:39], v[86:87], v[38:39]
	v_pk_mul_f32 v[42:43], v[34:35], v[32:33] op_sel_hi:[1,0]
; __device__ __forceinline__ unsigned cvt_pk_bf16(float lo, float hi) { unsigned r; asm volatile("v_cvt_pk_bf16_f32 %0, %1, %2" : "=v"(r) : "v"(lo), "v"(hi)); return r; }
; DI float x16_sum(float x) { const unsigned u = __builtin_bit_cast(unsigned, x); auto r = __builtin_amdgcn_permlane16_swap(u, u, false, false); return __builtin_bit_cast(float, (unsigned)r[0]) + __builtin_bit_cast(float, (unsigned)r[1]); }
; DI float x32_sum(float x) { const unsigned u = __builtin_bit_cast(unsigned, x); auto r = __builtin_amdgcn_permlane32_swap(u, u, false, false); return __builtin_bit_cast(float, (unsigned)r[0]) + __builtin_bit_cast(float, (unsigned)r[1]); }
;     __device__ __forceinline__ void operator()(const f32x4 (&acc)[2][2][4][2], const Unit& u, int wr, int wc, int fr, int fq) const {
;     ...
;             for (int ai = 0; ai < 2; ++ai)
; #pragma unroll
;                 for (int m = 0; m < 4; ++m) {
;                     const int r = row0 + ai * HALF + m * 16;
;                     const float rs = __builtin_amdgcn_rsqf((float)ss[r] * (1.0f / 1048576.0f) * (1.0f / 1024.0f) + EPS);
;                     f32x4 v[2][2]; float sq = 0.f;
; #pragma unroll
;                     for (int bj = 0; bj < 2; ++bj)
; #pragma unroll
;                         for (int n = 0; n < 2; ++n) { v[bj][n] = acc[ai][bj][m][n] * rs; sq += (v[bj][n][0] * v[bj][n][0] + v[bj][n][1] * v[bj][n][1]) + (v[bj][n][2] * v[bj][n][2] + v[bj][n][3] * v[bj][n][3]); }
;                     sq = x16_sum(sq); sq = x32_sum(sq);
;                     const float r2 = (sec < 2) ? qsc * __builtin_amdgcn_rsqf(sq * (1.0f / 64.0f) + EPS) : 1.0f;
;                     const int bl = r >> 13, t = r & 8191; const int pr = (bl << 13) + ((t & ((1 << dsh) - 1)) << (13 - dsh)) + (t >> dsh);
;                     bf16_t* rowp = O + (size_t)blk * SEC + (size_t)pr * 1024 + cin;
; #pragma unroll
;                     for (int bj = 0; bj < 2; ++bj) { const f32x4 v0 = v[bj][0] * gn[bj][0] * r2, v1 = v[bj][1] * gn[bj][1] * r2;
;                         u32x4 w; w.x = cvt_pk_bf16(v0[0], v0[1]); w.y = cvt_pk_bf16(v0[2], v0[3]); w.z = cvt_pk_bf16(v1[0], v1[1]); w.w = cvt_pk_bf16(v1[2], v1[3]);
;                         *(u32x4*)(rowp + bj * 32) = w; }
	v_pk_mul_f32 v[34:35], v[36:37], v[32:33] op_sel_hi:[1,0]
	v_pk_mul_f32 v[38:39], v[38:39], v[32:33] op_sel_hi:[1,0]
	v_pk_mul_f32 v[40:41], v[40:41], v[32:33] op_sel_hi:[1,0]
	s_nop 0
	v_cvt_pk_bf16_f32 v32, v40, v41
	v_cvt_pk_bf16_f32 v33, v38, v39
	v_cvt_pk_bf16_f32 v34, v34, v35
	v_cvt_pk_bf16_f32 v35, v42, v43
	v_mov_b32_dpp v180, v184 row_ror:8 row_mask:0xf bank_mask:0xf
	v_mov_b32_dpp v181, v185 row_ror:8 row_mask:0xf bank_mask:0xf
	v_mov_b32_dpp v182, v186 row_ror:8 row_mask:0xf bank_mask:0xf
	v_mov_b32_dpp v183, v187 row_ror:8 row_mask:0xf bank_mask:0xf
	v_lshl_add_u64 v[212:213], v[174:175], 0, v[218:219]
	v_mov_b32_dpp v184, v32 row_ror:8 row_mask:0xf bank_mask:0xc
	v_mov_b32_dpp v185, v33 row_ror:8 row_mask:0xf bank_mask:0xc
	v_mov_b32_dpp v186, v34 row_ror:8 row_mask:0xf bank_mask:0xc
	v_mov_b32_dpp v187, v35 row_ror:8 row_mask:0xf bank_mask:0xc
	v_lshl_add_u64 v[214:215], v[174:175], 0, v[220:221]
	v_cndmask_b32_e32 v32, v180, v32, vcc
	v_cndmask_b32_e32 v33, v181, v33, vcc
	v_cndmask_b32_e32 v34, v182, v34, vcc
	v_cndmask_b32_e32 v35, v183, v35, vcc
	s_nop 0
	global_store_dwordx4 v[212:213], v[184:187], off
	global_store_dwordx4 v[214:215], v[32:35], off
	v_lshl_add_u64 v[174:175], v[174:175], 0, v[176:177]
	s_nop 1
	v_add_u32_e32 v35, 0xa0, v160
	v_mov_b32_e32 v34, v248
	s_nop 0
	v_pk_mul_f32 v[30:31], v[30:31], v[34:35] op_sel_hi:[1,0]
	v_pk_mul_f32 v[222:223], v[30:31], v[30:31]
	v_pk_mul_f32 v[32:33], v[28:29], v[34:35] op_sel_hi:[1,0]
	v_pk_fma_f32 v[222:223], v[32:33], v[32:33], v[222:223]
	v_pk_mul_f32 v[26:27], v[26:27], v[34:35] op_sel_hi:[1,0]
	v_pk_fma_f32 v[222:223], v[26:27], v[26:27], v[222:223]
	v_pk_mul_f32 v[28:29], v[24:25], v[34:35] op_sel_hi:[1,0]
	v_pk_fma_f32 v[222:223], v[28:29], v[28:29], v[222:223]
	v_pk_mul_f32 v[22:23], v[22:23], v[34:35] op_sel_hi:[1,0]
	v_pk_fma_f32 v[222:223], v[22:23], v[22:23], v[222:223]
	v_pk_mul_f32 v[24:25], v[20:21], v[34:35] op_sel_hi:[1,0]
	v_pk_fma_f32 v[222:223], v[24:25], v[24:25], v[222:223]
	v_pk_mul_f32 v[18:19], v[18:19], v[34:35] op_sel_hi:[1,0]
	v_pk_fma_f32 v[222:223], v[18:19], v[18:19], v[222:223]
	v_pk_mul_f32 v[20:21], v[16:17], v[34:35] op_sel_hi:[1,0]
	v_pk_fma_f32 v[222:223], v[20:21], v[20:21], v[222:223]
	v_add_f32_e32 v16, v222, v223
	v_mov_b32_e32 v17, v16
	s_nop 1
	v_permlane16_swap_b32_e32 v16, v17
	v_add_f32_e32 v16, v16, v17
	v_mov_b32_e32 v17, v16
	s_nop 1
	v_permlane32_swap_b32_e32 v16, v17
	v_add_f32_e32 v16, v16, v17
	v_fmamk_f32 v16, v16, 0x3c800000, v229
	v_rsq_f32_e32 v16, v16
	s_nop 0
	v_mul_f32_e32 v16, v171, v16
	v_cndmask_b32_e64 v16, 1.0, v16, s[40:41]
	v_pk_mul_f32 v[32:33], v[92:93], v[32:33]
	v_pk_mul_f32 v[30:31], v[94:95], v[30:31]
	v_pk_mul_f32 v[28:29], v[88:89], v[28:29]
	v_pk_mul_f32 v[26:27], v[90:91], v[26:27]
	v_pk_mul_f32 v[30:31], v[30:31], v[16:17] op_sel_hi:[1,0]
	v_pk_mul_f32 v[32:33], v[32:33], v[16:17] op_sel_hi:[1,0]
	v_pk_mul_f32 v[36:37], v[26:27], v[16:17] op_sel_hi:[1,0]
	v_pk_mul_f32 v[28:29], v[28:29], v[16:17] op_sel_hi:[1,0]
	v_cvt_pk_bf16_f32 v184, v32, v33
	v_cvt_pk_bf16_f32 v185, v30, v31
	v_pk_mul_f32 v[20:21], v[80:81], v[20:21]
	v_pk_mul_f32 v[18:19], v[82:83], v[18:19]
	v_cvt_pk_bf16_f32 v186, v28, v29
	v_cvt_pk_bf16_f32 v187, v36, v37
	v_pk_mul_f32 v[24:25], v[84:85], v[24:25]
	v_pk_mul_f32 v[22:23], v[86:87], v[22:23]
	v_pk_mul_f32 v[26:27], v[18:19], v[16:17] op_sel_hi:[1,0]
	v_pk_mul_f32 v[18:19], v[20:21], v[16:17] op_sel_hi:[1,0]
	v_pk_mul_f32 v[22:23], v[22:23], v[16:17] op_sel_hi:[1,0]
	v_pk_mul_f32 v[24:25], v[24:25], v[16:17] op_sel_hi:[1,0]
	s_nop 0
	v_cvt_pk_bf16_f32 v16, v24, v25
	v_cvt_pk_bf16_f32 v17, v22, v23
	v_cvt_pk_bf16_f32 v18, v18, v19
	v_cvt_pk_bf16_f32 v19, v26, v27
	v_mov_b32_dpp v180, v184 row_ror:8 row_mask:0xf bank_mask:0xf
	v_mov_b32_dpp v181, v185 row_ror:8 row_mask:0xf bank_mask:0xf
	v_mov_b32_dpp v182, v186 row_ror:8 row_mask:0xf bank_mask:0xf
	v_mov_b32_dpp v183, v187 row_ror:8 row_mask:0xf bank_mask:0xf
; __device__ __forceinline__ unsigned cvt_pk_bf16(float lo, float hi) { unsigned r; asm volatile("v_cvt_pk_bf16_f32 %0, %1, %2" : "=v"(r) : "v"(lo), "v"(hi)); return r; }
; DI float x16_sum(float x) { const unsigned u = __builtin_bit_cast(unsigned, x); auto r = __builtin_amdgcn_permlane16_swap(u, u, false, false); return __builtin_bit_cast(float, (unsigned)r[0]) + __builtin_bit_cast(float, (unsigned)r[1]); }
; DI float x32_sum(float x) { const unsigned u = __builtin_bit_cast(unsigned, x); auto r = __builtin_amdgcn_permlane32_swap(u, u, false, false); return __builtin_bit_cast(float, (unsigned)r[0]) + __builtin_bit_cast(float, (unsigned)r[1]); }
;     __device__ __forceinline__ void operator()(const f32x4 (&acc)[2][2][4][2], const Unit& u, int wr, int wc, int fr, int fq) const {
;     ...
;             for (int ai = 0; ai < 2; ++ai)
; #pragma unroll
;                 for (int m = 0; m < 4; ++m) {
;                     const int r = row0 + ai * HALF + m * 16;
;                     const float rs = __builtin_amdgcn_rsqf((float)ss[r] * (1.0f / 1048576.0f) * (1.0f / 1024.0f) + EPS);
;                     f32x4 v[2][2]; float sq = 0.f;
; #pragma unroll
;                     for (int bj = 0; bj < 2; ++bj)
; #pragma unroll
;                         for (int n = 0; n < 2; ++n) { v[bj][n] = acc[ai][bj][m][n] * rs; sq += (v[bj][n][0] * v[bj][n][0] + v[bj][n][1] * v[bj][n][1]) + (v[bj][n][2] * v[bj][n][2] + v[bj][n][3] * v[bj][n][3]); }
;                     sq = x16_sum(sq); sq = x32_sum(sq);
;                     const float r2 = (sec < 2) ? qsc * __builtin_amdgcn_rsqf(sq * (1.0f / 64.0f) + EPS) : 1.0f;
;                     const int bl = r >> 13, t = r & 8191; const int pr = (bl << 13) + ((t & ((1 << dsh) - 1)) << (13 - dsh)) + (t >> dsh);
;                     bf16_t* rowp = O + (size_t)blk * SEC + (size_t)pr * 1024 + cin;
; #pragma unroll
;                     for (int bj = 0; bj < 2; ++bj) { const f32x4 v0 = v[bj][0] * gn[bj][0] * r2, v1 = v[bj][1] * gn[bj][1] * r2;
;                         u32x4 w; w.x = cvt_pk_bf16(v0[0], v0[1]); w.y = cvt_pk_bf16(v0[2], v0[3]); w.z = cvt_pk_bf16(v1[0], v1[1]); w.w = cvt_pk_bf16(v1[2], v1[3]);
;                         *(u32x4*)(rowp + bj * 32) = w; }
	v_lshl_add_u64 v[212:213], v[174:175], 0, v[218:219]
	v_mov_b32_dpp v184, v16 row_ror:8 row_mask:0xf bank_mask:0xc
	v_mov_b32_dpp v185, v17 row_ror:8 row_mask:0xf bank_mask:0xc
	v_mov_b32_dpp v186, v18 row_ror:8 row_mask:0xf bank_mask:0xc
	v_mov_b32_dpp v187, v19 row_ror:8 row_mask:0xf bank_mask:0xc
	v_lshl_add_u64 v[214:215], v[174:175], 0, v[220:221]
	v_cndmask_b32_e32 v16, v180, v16, vcc
	v_cndmask_b32_e32 v17, v181, v17, vcc
	v_cndmask_b32_e32 v18, v182, v18, vcc
	v_cndmask_b32_e32 v19, v183, v19, vcc
	s_nop 0
	global_store_dwordx4 v[212:213], v[184:187], off
	global_store_dwordx4 v[214:215], v[16:19], off
	v_lshl_add_u64 v[174:175], v[174:175], 0, v[176:177]
	s_nop 1
	v_add_u32_e32 v19, 0xb0, v160
	v_mov_b32_e32 v18, v249
	s_nop 0
	v_pk_mul_f32 v[14:15], v[14:15], v[18:19] op_sel_hi:[1,0]
	v_pk_mul_f32 v[222:223], v[14:15], v[14:15]
	v_pk_mul_f32 v[16:17], v[12:13], v[18:19] op_sel_hi:[1,0]
	v_pk_fma_f32 v[222:223], v[16:17], v[16:17], v[222:223]
	v_pk_mul_f32 v[10:11], v[10:11], v[18:19] op_sel_hi:[1,0]
	v_pk_fma_f32 v[222:223], v[10:11], v[10:11], v[222:223]
	v_pk_mul_f32 v[12:13], v[8:9], v[18:19] op_sel_hi:[1,0]
	v_pk_fma_f32 v[222:223], v[12:13], v[12:13], v[222:223]
	v_pk_mul_f32 v[6:7], v[6:7], v[18:19] op_sel_hi:[1,0]
	v_pk_fma_f32 v[222:223], v[6:7], v[6:7], v[222:223]
	v_pk_mul_f32 v[8:9], v[4:5], v[18:19] op_sel_hi:[1,0]
	v_pk_fma_f32 v[222:223], v[8:9], v[8:9], v[222:223]
	v_pk_mul_f32 v[2:3], v[2:3], v[18:19] op_sel_hi:[1,0]
	v_pk_fma_f32 v[222:223], v[2:3], v[2:3], v[222:223]
	v_pk_mul_f32 v[4:5], v[0:1], v[18:19] op_sel_hi:[1,0]
	v_pk_fma_f32 v[222:223], v[4:5], v[4:5], v[222:223]
	v_add_f32_e32 v0, v222, v223
	v_mov_b32_e32 v1, v0
	s_nop 1
	v_permlane16_swap_b32_e32 v0, v1
	v_add_f32_e32 v0, v0, v1
	v_mov_b32_e32 v1, v0
	s_nop 1
	v_permlane32_swap_b32_e32 v0, v1
	v_add_f32_e32 v0, v0, v1
	v_fmamk_f32 v0, v0, 0x3c800000, v229
	v_rsq_f32_e32 v0, v0
	s_nop 0
	v_mul_f32_e32 v0, v171, v0
	v_cndmask_b32_e64 v0, 1.0, v0, s[40:41]
	v_pk_mul_f32 v[16:17], v[92:93], v[16:17]
	v_pk_mul_f32 v[14:15], v[94:95], v[14:15]
	v_pk_mul_f32 v[12:13], v[88:89], v[12:13]
	v_pk_mul_f32 v[10:11], v[90:91], v[10:11]
	v_pk_mul_f32 v[14:15], v[14:15], v[0:1] op_sel_hi:[1,0]
	v_pk_mul_f32 v[16:17], v[16:17], v[0:1] op_sel_hi:[1,0]
	v_pk_mul_f32 v[20:21], v[10:11], v[0:1] op_sel_hi:[1,0]
	v_pk_mul_f32 v[12:13], v[12:13], v[0:1] op_sel_hi:[1,0]
	v_cvt_pk_bf16_f32 v184, v16, v17
	v_cvt_pk_bf16_f32 v185, v14, v15
	v_pk_mul_f32 v[4:5], v[80:81], v[4:5]
	v_pk_mul_f32 v[2:3], v[82:83], v[2:3]
	v_cvt_pk_bf16_f32 v186, v12, v13
	v_cvt_pk_bf16_f32 v187, v20, v21
	v_pk_mul_f32 v[8:9], v[84:85], v[8:9]
	v_pk_mul_f32 v[6:7], v[86:87], v[6:7]
	v_pk_mul_f32 v[10:11], v[2:3], v[0:1] op_sel_hi:[1,0]
	v_pk_mul_f32 v[2:3], v[4:5], v[0:1] op_sel_hi:[1,0]
	v_pk_mul_f32 v[6:7], v[6:7], v[0:1] op_sel_hi:[1,0]
	v_pk_mul_f32 v[8:9], v[8:9], v[0:1] op_sel_hi:[1,0]
	s_nop 0
	v_cvt_pk_bf16_f32 v0, v8, v9
	v_cvt_pk_bf16_f32 v1, v6, v7
	v_cvt_pk_bf16_f32 v2, v2, v3
	v_cvt_pk_bf16_f32 v3, v10, v11
	v_mov_b32_dpp v180, v184 row_ror:8 row_mask:0xf bank_mask:0xf
	v_mov_b32_dpp v181, v185 row_ror:8 row_mask:0xf bank_mask:0xf
	v_mov_b32_dpp v182, v186 row_ror:8 row_mask:0xf bank_mask:0xf
	v_mov_b32_dpp v183, v187 row_ror:8 row_mask:0xf bank_mask:0xf
	v_lshl_add_u64 v[212:213], v[174:175], 0, v[218:219]
	v_mov_b32_dpp v184, v0 row_ror:8 row_mask:0xf bank_mask:0xc
	v_mov_b32_dpp v185, v1 row_ror:8 row_mask:0xf bank_mask:0xc
	v_mov_b32_dpp v186, v2 row_ror:8 row_mask:0xf bank_mask:0xc
	v_mov_b32_dpp v187, v3 row_ror:8 row_mask:0xf bank_mask:0xc
	v_lshl_add_u64 v[214:215], v[174:175], 0, v[220:221]
	v_cndmask_b32_e32 v0, v180, v0, vcc
	v_cndmask_b32_e32 v1, v181, v1, vcc
	v_cndmask_b32_e32 v2, v182, v2, vcc
	v_cndmask_b32_e32 v3, v183, v3, vcc
	s_nop 0
	global_store_dwordx4 v[212:213], v[184:187], off
	global_store_dwordx4 v[214:215], v[0:3], off
	s_andn2_b64 vcc, exec, s[38:39]
	s_mov_b64 s[0:1], -1
	s_cbranch_vccnz .LBB0_350

; __device__ __forceinline__ unsigned cvt_pk_bf16(float lo, float hi) { unsigned r; asm volatile("v_cvt_pk_bf16_f32 %0, %1, %2" : "=v"(r) : "v"(lo), "v"(hi)); return r; }
;     __device__ __forceinline__ void operator()(const f32x4 (&acc)[2][2][4][2], const Unit& u, int wr, int wc, int fr, int fq) const {
;     ...
;             const int blk = colt >> 10, g = blk % 3, sec = blk / 3; const int dsh = (g == 0) ? 0 : (g == 1 ? 2 : 4); const int cin = (colt & 1023) + 64 * wc + 8 * fq;
;             f32x4 gn[2][2];
;             const float* gp = (sec == 0) ? qg + g * 64 : kg + g * 64;
; #pragma unroll
;             for (int bj = 0; bj < 2; ++bj)
; #pragma unroll
;                 for (int n = 0; n < 2; ++n) gn[bj][n] = (sec < 2) ? *(const f32x4*)(gp + 32 * bj + 8 * fq + 4 * n) : (f32x4){1.f, 1.f, 1.f, 1.f};
;             const float qsc = (sec == 0) ? 0.125f * 1.4426950408889634f : 1.0f;
; #pragma unroll
;             for (int ai = 0; ai < 2; ++ai)
; #pragma unroll
;                 for (int m = 0; m < 4; ++m) {
;                     const int r = row0 + ai * HALF + m * 16;
;                     const float rs = __builtin_amdgcn_rsqf((float)ss[r] * (1.0f / 1048576.0f) * (1.0f / 1024.0f) + EPS);
;                     f32x4 v[2][2]; float sq = 0.f;
; #pragma unroll
;                     for (int bj = 0; bj < 2; ++bj)
; #pragma unroll
;                         for (int n = 0; n < 2; ++n) { v[bj][n] = acc[ai][bj][m][n] * rs; sq += (v[bj][n][0] * v[bj][n][0] + v[bj][n][1] * v[bj][n][1]) + (v[bj][n][2] * v[bj][n][2] + v[bj][n][3] * v[bj][n][3]); }
;                     sq = x16_sum(sq); sq = x32_sum(sq);
;                     const float r2 = (sec < 2) ? qsc * __builtin_amdgcn_rsqf(sq * (1.0f / 64.0f) + EPS) : 1.0f;
;                     const int bl = r >> 13, t = r & 8191; const int pr = (bl << 13) + ((t & ((1 << dsh) - 1)) << (13 - dsh)) + (t >> dsh);
;                     bf16_t* rowp = O + (size_t)blk * SEC + (size_t)pr * 1024 + cin;
; #pragma unroll
;                     for (int bj = 0; bj < 2; ++bj) { const f32x4 v0 = v[bj][0] * gn[bj][0] * r2, v1 = v[bj][1] * gn[bj][1] * r2;
;                         u32x4 w; w.x = cvt_pk_bf16(v0[0], v0[1]); w.y = cvt_pk_bf16(v0[2], v0[3]); w.z = cvt_pk_bf16(v1[0], v1[1]); w.w = cvt_pk_bf16(v1[2], v1[3]);
;                         *(u32x4*)(rowp + bj * 32) = w; }
.Lv433:
	s_mov_b32 vcc_lo, 0xff00ff00
	s_mov_b32 vcc_hi, 0xff00ff00
	s_nop 1
	v_lshl_add_u64 v[162:163], v[160:161], 3, s[48:49]
	s_cmp_eq_u32 s2, 1
	s_cselect_b32 s34, 2, 4
	s_cmp_lg_u32 s2, 0
	v_cndmask_b32_e64 v171, 1.0, v234, s[0:1]
	s_cselect_b32 s34, s34, 0
	s_sub_i32 s42, 13, s34
	s_and_b32 s43, s69, 0xffffe000
	s_ashr_i32 s89, s88, 31
	s_and_b32 s2, s76, 0x300
	s_lshl_b64 s[0:1], s[88:89], 25
	s_add_u32 s0, s28, s0
	v_or_b32_e32 v172, s2, v169
	s_addc_u32 s1, s29, s1
	s_movk_i32 s2, 0x1fdf
	s_mov_b32 s88, 0x1000
	s_cmp_eq_u32 s34, 0
	s_cselect_b32 s88, 0x4000, s88
	s_cmp_eq_u32 s34, 4
	s_cselect_b32 s88, 0x800000, s88
	s_lshr_b32 s89, 0x8000, s34
	v_mov_b32_e32 v220, s88
	v_mov_b32_e32 v176, s89
	s_mul_i32 s89, s89, 5
	v_mov_b32_e32 v177, 0
	v_sub_u32_e32 v218, 64, v220
	v_mov_b32_e32 v178, s89
	v_mov_b32_e32 v179, 0
	v_cndmask_b32_e64 v219, 0, -1, vcc
	v_cndmask_b32_e64 v218, 0, v218, vcc
	v_cndmask_b32_e64 v220, v220, 64, vcc
	v_mov_b32_e32 v221, 0
	s_waitcnt vmcnt(0)
	v_readlane_b32 s88, v250, 51
	s_nop 1
	s_cmp_eq_u32 s88, 0
	s_cbranch_scc1 .Lss_nc_c
	v_cvt_f32_u32_e32 v223, v193
	v_cvt_f32_u32_e32 v222, v192
	v_fmamk_f32 v222, v223, 0x4f800000, v222
	v_fmamk_f32 v222, v222, 0x30800000, v229
	v_rsq_f32_e32 v242, v222
	v_cvt_f32_u32_e32 v223, v195
	v_cvt_f32_u32_e32 v222, v194
	v_fmamk_f32 v222, v223, 0x4f800000, v222
	v_fmamk_f32 v222, v222, 0x30800000, v229
	v_rsq_f32_e32 v243, v222
	v_cvt_f32_u32_e32 v223, v197
	v_cvt_f32_u32_e32 v222, v196
	v_fmamk_f32 v222, v223, 0x4f800000, v222
	v_fmamk_f32 v222, v222, 0x30800000, v229
	v_rsq_f32_e32 v244, v222
	v_cvt_f32_u32_e32 v223, v199
	v_cvt_f32_u32_e32 v222, v198
	v_fmamk_f32 v222, v223, 0x4f800000, v222
	v_fmamk_f32 v222, v222, 0x30800000, v229
	v_rsq_f32_e32 v245, v222
	v_cvt_f32_u32_e32 v223, v201
	v_cvt_f32_u32_e32 v222, v200
	v_fmamk_f32 v222, v223, 0x4f800000, v222
	v_fmamk_f32 v222, v222, 0x30800000, v229
	v_rsq_f32_e32 v246, v222
	v_cvt_f32_u32_e32 v223, v203
	v_cvt_f32_u32_e32 v222, v202
	v_fmamk_f32 v222, v223, 0x4f800000, v222
	v_fmamk_f32 v222, v222, 0x30800000, v229
	v_rsq_f32_e32 v247, v222
	v_cvt_f32_u32_e32 v223, v205
	v_cvt_f32_u32_e32 v222, v204
	v_fmamk_f32 v222, v223, 0x4f800000, v222
	v_fmamk_f32 v222, v222, 0x30800000, v229
	v_rsq_f32_e32 v248, v222
	v_cvt_f32_u32_e32 v223, v207
	v_cvt_f32_u32_e32 v222, v206
	v_fmamk_f32 v222, v223, 0x4f800000, v222
	v_fmamk_f32 v222, v222, 0x30800000, v229
	v_rsq_f32_e32 v249, v222
	v_writelane_b32 v250, 0, 51
.Lss_nc_c:
	s_nop 1
	v_mov_b32_e32 v112, v242
	s_nop 0
	v_pk_mul_f32 v[144:145], v[144:145], v[112:113] op_sel_hi:[1,0]
	v_pk_mul_f32 v[164:165], v[142:143], v[112:113] op_sel_hi:[1,0]
	v_pk_mul_f32 v[140:141], v[140:141], v[112:113] op_sel_hi:[1,0]
	v_pk_mul_f32 v[142:143], v[138:139], v[112:113] op_sel_hi:[1,0]
	v_pk_mul_f32 v[136:137], v[136:137], v[112:113] op_sel_hi:[1,0]
	v_pk_mul_f32 v[138:139], v[134:135], v[112:113] op_sel_hi:[1,0]
	v_pk_mul_f32 v[132:133], v[132:133], v[112:113] op_sel_hi:[1,0]
	v_pk_mul_f32 v[134:135], v[130:131], v[112:113] op_sel_hi:[1,0]
	v_lshlrev_b32_e32 v131, s42, v160
	v_and_b32_e32 v131, 0x1ffe, v131
	v_and_b32_e32 v112, 0x1fcf, v160
	v_lshrrev_b32_e32 v112, s34, v112
	v_or_b32_e32 v112, s43, v112
	v_add_u32_e32 v166, v112, v131
	v_ashrrev_i32_e32 v167, 31, v166
	v_lshlrev_b64 v[166:167], 11, v[166:167]
	v_lshl_add_u64 v[166:167], s[0:1], 0, v[166:167]
	v_lshlrev_b32_e32 v112, 1, v172
	v_lshl_add_u64 v[166:167], v[166:167], 0, v[112:113]
	v_cvt_pk_bf16_f32 v184, v164, v165
	v_cvt_pk_bf16_f32 v185, v144, v145
	v_cvt_pk_bf16_f32 v186, v142, v143
	v_cvt_pk_bf16_f32 v187, v140, v141
	s_nop 0
	v_cvt_pk_bf16_f32 v208, v138, v139
	v_cvt_pk_bf16_f32 v209, v136, v137
	v_cvt_pk_bf16_f32 v210, v134, v135
	v_cvt_pk_bf16_f32 v211, v132, v133
	v_mov_b32_dpp v180, v184 row_ror:8 row_mask:0xf bank_mask:0xf
	v_mov_b32_dpp v181, v185 row_ror:8 row_mask:0xf bank_mask:0xf
	v_mov_b32_dpp v182, v186 row_ror:8 row_mask:0xf bank_mask:0xf
	v_mov_b32_dpp v183, v187 row_ror:8 row_mask:0xf bank_mask:0xf
	v_lshl_add_u64 v[212:213], v[166:167], 0, v[218:219]
	v_mov_b32_dpp v184, v208 row_ror:8 row_mask:0xf bank_mask:0xc
	v_mov_b32_dpp v185, v209 row_ror:8 row_mask:0xf bank_mask:0xc
	v_mov_b32_dpp v186, v210 row_ror:8 row_mask:0xf bank_mask:0xc
	v_mov_b32_dpp v187, v211 row_ror:8 row_mask:0xf bank_mask:0xc
	v_lshl_add_u64 v[214:215], v[166:167], 0, v[220:221]
	v_cndmask_b32_e32 v208, v180, v208, vcc
	v_cndmask_b32_e32 v209, v181, v209, vcc
	v_cndmask_b32_e32 v210, v182, v210, vcc
	v_cndmask_b32_e32 v211, v183, v211, vcc
	s_nop 0
	global_store_dwordx4 v[212:213], v[184:187], off
	global_store_dwordx4 v[214:215], v[208:211], off
	v_lshl_add_u64 v[174:175], v[166:167], 0, v[176:177]
	s_nop 1
	v_or_b32_e32 v133, 16, v160
	v_mov_b32_e32 v132, v243
	s_nop 0
	v_pk_mul_f32 v[128:129], v[128:129], v[132:133] op_sel_hi:[1,0]
	v_pk_mul_f32 v[130:131], v[126:127], v[132:133] op_sel_hi:[1,0]
	v_pk_mul_f32 v[124:125], v[124:125], v[132:133] op_sel_hi:[1,0]
	v_pk_mul_f32 v[126:127], v[122:123], v[132:133] op_sel_hi:[1,0]
	v_pk_mul_f32 v[120:121], v[120:121], v[132:133] op_sel_hi:[1,0]
	v_pk_mul_f32 v[122:123], v[118:119], v[132:133] op_sel_hi:[1,0]
	v_pk_mul_f32 v[116:117], v[116:117], v[132:133] op_sel_hi:[1,0]
	v_pk_mul_f32 v[118:119], v[114:115], v[132:133] op_sel_hi:[1,0]
	s_nop 0
	v_cvt_pk_bf16_f32 v184, v130, v131
	v_cvt_pk_bf16_f32 v185, v128, v129
	v_cvt_pk_bf16_f32 v186, v126, v127
	v_cvt_pk_bf16_f32 v187, v124, v125
	s_movk_i32 s2, 0x1fef
	v_cvt_pk_bf16_f32 v208, v122, v123
	v_cvt_pk_bf16_f32 v209, v120, v121
	v_cvt_pk_bf16_f32 v210, v118, v119
	v_cvt_pk_bf16_f32 v211, v116, v117
	v_mov_b32_dpp v180, v184 row_ror:8 row_mask:0xf bank_mask:0xf
; __device__ __forceinline__ unsigned cvt_pk_bf16(float lo, float hi) { unsigned r; asm volatile("v_cvt_pk_bf16_f32 %0, %1, %2" : "=v"(r) : "v"(lo), "v"(hi)); return r; }
; DI float x16_sum(float x) { const unsigned u = __builtin_bit_cast(unsigned, x); auto r = __builtin_amdgcn_permlane16_swap(u, u, false, false); return __builtin_bit_cast(float, (unsigned)r[0]) + __builtin_bit_cast(float, (unsigned)r[1]); }
; DI float x32_sum(float x) { const unsigned u = __builtin_bit_cast(unsigned, x); auto r = __builtin_amdgcn_permlane32_swap(u, u, false, false); return __builtin_bit_cast(float, (unsigned)r[0]) + __builtin_bit_cast(float, (unsigned)r[1]); }
;     __device__ __forceinline__ void operator()(const f32x4 (&acc)[2][2][4][2], const Unit& u, int wr, int wc, int fr, int fq) const {
;     ...
;             for (int ai = 0; ai < 2; ++ai)
; #pragma unroll
;                 for (int m = 0; m < 4; ++m) {
;                     const int r = row0 + ai * HALF + m * 16;
;                     const float rs = __builtin_amdgcn_rsqf((float)ss[r] * (1.0f / 1048576.0f) * (1.0f / 1024.0f) + EPS);
;                     f32x4 v[2][2]; float sq = 0.f;
; #pragma unroll
;                     for (int bj = 0; bj < 2; ++bj)
; #pragma unroll
;                         for (int n = 0; n < 2; ++n) { v[bj][n] = acc[ai][bj][m][n] * rs; sq += (v[bj][n][0] * v[bj][n][0] + v[bj][n][1] * v[bj][n][1]) + (v[bj][n][2] * v[bj][n][2] + v[bj][n][3] * v[bj][n][3]); }
;                     sq = x16_sum(sq); sq = x32_sum(sq);
;                     const float r2 = (sec < 2) ? qsc * __builtin_amdgcn_rsqf(sq * (1.0f / 64.0f) + EPS) : 1.0f;
;                     const int bl = r >> 13, t = r & 8191; const int pr = (bl << 13) + ((t & ((1 << dsh) - 1)) << (13 - dsh)) + (t >> dsh);
;                     bf16_t* rowp = O + (size_t)blk * SEC + (size_t)pr * 1024 + cin;
; #pragma unroll
;                     for (int bj = 0; bj < 2; ++bj) { const f32x4 v0 = v[bj][0] * gn[bj][0] * r2, v1 = v[bj][1] * gn[bj][1] * r2;
;                         u32x4 w; w.x = cvt_pk_bf16(v0[0], v0[1]); w.y = cvt_pk_bf16(v0[2], v0[3]); w.z = cvt_pk_bf16(v1[0], v1[1]); w.w = cvt_pk_bf16(v1[2], v1[3]);
;                         *(u32x4*)(rowp + bj * 32) = w; }
	v_mov_b32_dpp v181, v185 row_ror:8 row_mask:0xf bank_mask:0xf
	v_mov_b32_dpp v182, v186 row_ror:8 row_mask:0xf bank_mask:0xf
	v_mov_b32_dpp v183, v187 row_ror:8 row_mask:0xf bank_mask:0xf
	v_lshl_add_u64 v[212:213], v[174:175], 0, v[218:219]
	v_mov_b32_dpp v184, v208 row_ror:8 row_mask:0xf bank_mask:0xc
	v_mov_b32_dpp v185, v209 row_ror:8 row_mask:0xf bank_mask:0xc
	v_mov_b32_dpp v186, v210 row_ror:8 row_mask:0xf bank_mask:0xc
	v_mov_b32_dpp v187, v211 row_ror:8 row_mask:0xf bank_mask:0xc
	v_lshl_add_u64 v[214:215], v[174:175], 0, v[220:221]
	v_cndmask_b32_e32 v208, v180, v208, vcc
	v_cndmask_b32_e32 v209, v181, v209, vcc
	v_cndmask_b32_e32 v210, v182, v210, vcc
	v_cndmask_b32_e32 v211, v183, v211, vcc
	s_nop 0
	global_store_dwordx4 v[212:213], v[184:187], off
	global_store_dwordx4 v[214:215], v[208:211], off
	v_lshl_add_u64 v[174:175], v[174:175], 0, v[176:177]
	s_nop 1
	v_or_b32_e32 v117, 32, v160
	v_mov_b32_e32 v116, v244
	s_nop 0
	v_pk_mul_f32 v[110:111], v[110:111], v[116:117] op_sel_hi:[1,0]
	v_pk_mul_f32 v[114:115], v[108:109], v[116:117] op_sel_hi:[1,0]
	v_pk_mul_f32 v[106:107], v[106:107], v[116:117] op_sel_hi:[1,0]
	v_pk_mul_f32 v[108:109], v[104:105], v[116:117] op_sel_hi:[1,0]
	v_pk_mul_f32 v[102:103], v[102:103], v[116:117] op_sel_hi:[1,0]
	v_pk_mul_f32 v[104:105], v[100:101], v[116:117] op_sel_hi:[1,0]
	v_pk_mul_f32 v[98:99], v[98:99], v[116:117] op_sel_hi:[1,0]
	v_pk_mul_f32 v[100:101], v[96:97], v[116:117] op_sel_hi:[1,0]
	s_nop 0
	v_cvt_pk_bf16_f32 v184, v114, v115
	v_cvt_pk_bf16_f32 v185, v110, v111
	v_cvt_pk_bf16_f32 v186, v108, v109
	v_cvt_pk_bf16_f32 v187, v106, v107
	s_movk_i32 s2, 0x1fff
	v_cvt_pk_bf16_f32 v208, v104, v105
	v_cvt_pk_bf16_f32 v209, v102, v103
	v_cvt_pk_bf16_f32 v210, v100, v101
	v_cvt_pk_bf16_f32 v211, v98, v99
	v_mov_b32_dpp v180, v184 row_ror:8 row_mask:0xf bank_mask:0xf
	v_mov_b32_dpp v181, v185 row_ror:8 row_mask:0xf bank_mask:0xf
	v_mov_b32_dpp v182, v186 row_ror:8 row_mask:0xf bank_mask:0xf
	v_mov_b32_dpp v183, v187 row_ror:8 row_mask:0xf bank_mask:0xf
	v_lshl_add_u64 v[212:213], v[174:175], 0, v[218:219]
	v_mov_b32_dpp v184, v208 row_ror:8 row_mask:0xf bank_mask:0xc
	v_mov_b32_dpp v185, v209 row_ror:8 row_mask:0xf bank_mask:0xc
	v_mov_b32_dpp v186, v210 row_ror:8 row_mask:0xf bank_mask:0xc
	v_mov_b32_dpp v187, v211 row_ror:8 row_mask:0xf bank_mask:0xc
	v_lshl_add_u64 v[214:215], v[174:175], 0, v[220:221]
	v_cndmask_b32_e32 v208, v180, v208, vcc
	v_cndmask_b32_e32 v209, v181, v209, vcc
	v_cndmask_b32_e32 v210, v182, v210, vcc
	v_cndmask_b32_e32 v211, v183, v211, vcc
	s_nop 0
	global_store_dwordx4 v[212:213], v[184:187], off
	global_store_dwordx4 v[214:215], v[208:211], off
	v_lshl_add_u64 v[174:175], v[174:175], 0, v[176:177]
	s_nop 1
	v_or_b32_e32 v99, 48, v160
	v_mov_b32_e32 v98, v245
	s_nop 0
	v_pk_mul_f32 v[78:79], v[78:79], v[98:99] op_sel_hi:[1,0]
	v_pk_mul_f32 v[96:97], v[76:77], v[98:99] op_sel_hi:[1,0]
	v_pk_mul_f32 v[74:75], v[74:75], v[98:99] op_sel_hi:[1,0]
	v_pk_mul_f32 v[76:77], v[72:73], v[98:99] op_sel_hi:[1,0]
	v_pk_mul_f32 v[70:71], v[70:71], v[98:99] op_sel_hi:[1,0]
	v_pk_mul_f32 v[72:73], v[68:69], v[98:99] op_sel_hi:[1,0]
	v_pk_mul_f32 v[66:67], v[66:67], v[98:99] op_sel_hi:[1,0]
	v_pk_mul_f32 v[68:69], v[64:65], v[98:99] op_sel_hi:[1,0]
	s_nop 0
	v_cvt_pk_bf16_f32 v184, v96, v97
	v_cvt_pk_bf16_f32 v185, v78, v79
	v_cvt_pk_bf16_f32 v186, v76, v77
	v_cvt_pk_bf16_f32 v187, v74, v75
	s_nop 0
	v_cvt_pk_bf16_f32 v208, v72, v73
	v_cvt_pk_bf16_f32 v209, v70, v71
	v_cvt_pk_bf16_f32 v210, v68, v69
	v_cvt_pk_bf16_f32 v211, v66, v67
	v_mov_b32_dpp v180, v184 row_ror:8 row_mask:0xf bank_mask:0xf
	v_mov_b32_dpp v181, v185 row_ror:8 row_mask:0xf bank_mask:0xf
	v_mov_b32_dpp v182, v186 row_ror:8 row_mask:0xf bank_mask:0xf
	v_mov_b32_dpp v183, v187 row_ror:8 row_mask:0xf bank_mask:0xf
	v_lshl_add_u64 v[212:213], v[174:175], 0, v[218:219]
	v_mov_b32_dpp v184, v208 row_ror:8 row_mask:0xf bank_mask:0xc
	v_mov_b32_dpp v185, v209 row_ror:8 row_mask:0xf bank_mask:0xc
	v_mov_b32_dpp v186, v210 row_ror:8 row_mask:0xf bank_mask:0xc
	v_mov_b32_dpp v187, v211 row_ror:8 row_mask:0xf bank_mask:0xc
	v_lshl_add_u64 v[214:215], v[174:175], 0, v[220:221]
	v_cndmask_b32_e32 v208, v180, v208, vcc
	v_cndmask_b32_e32 v209, v181, v209, vcc
	v_cndmask_b32_e32 v210, v182, v210, vcc
	v_cndmask_b32_e32 v211, v183, v211, vcc
	s_nop 0
	global_store_dwordx4 v[212:213], v[184:187], off
	global_store_dwordx4 v[214:215], v[208:211], off
	v_lshl_add_u64 v[174:175], v[174:175], 0, v[178:179]
	s_nop 1
	v_add_u32_e32 v67, 0x80, v160
	v_mov_b32_e32 v66, v246
	s_nop 0
	v_pk_mul_f32 v[62:63], v[62:63], v[66:67] op_sel_hi:[1,0]
	v_pk_mul_f32 v[64:65], v[60:61], v[66:67] op_sel_hi:[1,0]
	v_pk_mul_f32 v[58:59], v[58:59], v[66:67] op_sel_hi:[1,0]
	v_pk_mul_f32 v[60:61], v[56:57], v[66:67] op_sel_hi:[1,0]
	v_pk_mul_f32 v[54:55], v[54:55], v[66:67] op_sel_hi:[1,0]
	v_pk_mul_f32 v[56:57], v[52:53], v[66:67] op_sel_hi:[1,0]
	v_pk_mul_f32 v[50:51], v[50:51], v[66:67] op_sel_hi:[1,0]
	v_pk_mul_f32 v[52:53], v[48:49], v[66:67] op_sel_hi:[1,0]
	s_nop 0
	v_cvt_pk_bf16_f32 v184, v64, v65
	v_cvt_pk_bf16_f32 v185, v62, v63
	v_cvt_pk_bf16_f32 v186, v60, v61
	v_cvt_pk_bf16_f32 v187, v58, v59
	s_nop 0
	v_cvt_pk_bf16_f32 v208, v56, v57
	v_cvt_pk_bf16_f32 v209, v54, v55
	v_cvt_pk_bf16_f32 v210, v52, v53
	v_cvt_pk_bf16_f32 v211, v50, v51
	v_mov_b32_dpp v180, v184 row_ror:8 row_mask:0xf bank_mask:0xf
	v_mov_b32_dpp v181, v185 row_ror:8 row_mask:0xf bank_mask:0xf
	v_mov_b32_dpp v182, v186 row_ror:8 row_mask:0xf bank_mask:0xf
	v_mov_b32_dpp v183, v187 row_ror:8 row_mask:0xf bank_mask:0xf
	v_lshl_add_u64 v[212:213], v[174:175], 0, v[218:219]
; __device__ __forceinline__ unsigned cvt_pk_bf16(float lo, float hi) { unsigned r; asm volatile("v_cvt_pk_bf16_f32 %0, %1, %2" : "=v"(r) : "v"(lo), "v"(hi)); return r; }
; DI float x16_sum(float x) { const unsigned u = __builtin_bit_cast(unsigned, x); auto r = __builtin_amdgcn_permlane16_swap(u, u, false, false); return __builtin_bit_cast(float, (unsigned)r[0]) + __builtin_bit_cast(float, (unsigned)r[1]); }
; DI float x32_sum(float x) { const unsigned u = __builtin_bit_cast(unsigned, x); auto r = __builtin_amdgcn_permlane32_swap(u, u, false, false); return __builtin_bit_cast(float, (unsigned)r[0]) + __builtin_bit_cast(float, (unsigned)r[1]); }
;     __device__ __forceinline__ void operator()(const f32x4 (&acc)[2][2][4][2], const Unit& u, int wr, int wc, int fr, int fq) const {
;     ...
;             for (int ai = 0; ai < 2; ++ai)
; #pragma unroll
;                 for (int m = 0; m < 4; ++m) {
;                     const int r = row0 + ai * HALF + m * 16;
;                     const float rs = __builtin_amdgcn_rsqf((float)ss[r] * (1.0f / 1048576.0f) * (1.0f / 1024.0f) + EPS);
;                     f32x4 v[2][2]; float sq = 0.f;
; #pragma unroll
;                     for (int bj = 0; bj < 2; ++bj)
; #pragma unroll
;                         for (int n = 0; n < 2; ++n) { v[bj][n] = acc[ai][bj][m][n] * rs; sq += (v[bj][n][0] * v[bj][n][0] + v[bj][n][1] * v[bj][n][1]) + (v[bj][n][2] * v[bj][n][2] + v[bj][n][3] * v[bj][n][3]); }
;                     sq = x16_sum(sq); sq = x32_sum(sq);
;                     const float r2 = (sec < 2) ? qsc * __builtin_amdgcn_rsqf(sq * (1.0f / 64.0f) + EPS) : 1.0f;
;                     const int bl = r >> 13, t = r & 8191; const int pr = (bl << 13) + ((t & ((1 << dsh) - 1)) << (13 - dsh)) + (t >> dsh);
;                     bf16_t* rowp = O + (size_t)blk * SEC + (size_t)pr * 1024 + cin;
; #pragma unroll
;                     for (int bj = 0; bj < 2; ++bj) { const f32x4 v0 = v[bj][0] * gn[bj][0] * r2, v1 = v[bj][1] * gn[bj][1] * r2;
;                         u32x4 w; w.x = cvt_pk_bf16(v0[0], v0[1]); w.y = cvt_pk_bf16(v0[2], v0[3]); w.z = cvt_pk_bf16(v1[0], v1[1]); w.w = cvt_pk_bf16(v1[2], v1[3]);
;                         *(u32x4*)(rowp + bj * 32) = w; }
	v_mov_b32_dpp v184, v208 row_ror:8 row_mask:0xf bank_mask:0xc
	v_mov_b32_dpp v185, v209 row_ror:8 row_mask:0xf bank_mask:0xc
	v_mov_b32_dpp v186, v210 row_ror:8 row_mask:0xf bank_mask:0xc
	v_mov_b32_dpp v187, v211 row_ror:8 row_mask:0xf bank_mask:0xc
	v_lshl_add_u64 v[214:215], v[174:175], 0, v[220:221]
	v_cndmask_b32_e32 v208, v180, v208, vcc
	v_cndmask_b32_e32 v209, v181, v209, vcc
	v_cndmask_b32_e32 v210, v182, v210, vcc
	v_cndmask_b32_e32 v211, v183, v211, vcc
	s_nop 0
	global_store_dwordx4 v[212:213], v[184:187], off
	global_store_dwordx4 v[214:215], v[208:211], off
	v_lshl_add_u64 v[174:175], v[174:175], 0, v[176:177]
	s_nop 1
	v_add_u32_e32 v51, 0x90, v160
	v_mov_b32_e32 v50, v247
	s_nop 0
	v_pk_mul_f32 v[46:47], v[46:47], v[50:51] op_sel_hi:[1,0]
	v_pk_mul_f32 v[48:49], v[44:45], v[50:51] op_sel_hi:[1,0]
	v_pk_mul_f32 v[42:43], v[42:43], v[50:51] op_sel_hi:[1,0]
	v_pk_mul_f32 v[44:45], v[40:41], v[50:51] op_sel_hi:[1,0]
	v_pk_mul_f32 v[38:39], v[38:39], v[50:51] op_sel_hi:[1,0]
	v_pk_mul_f32 v[40:41], v[36:37], v[50:51] op_sel_hi:[1,0]
	v_pk_mul_f32 v[34:35], v[34:35], v[50:51] op_sel_hi:[1,0]
	v_pk_mul_f32 v[36:37], v[32:33], v[50:51] op_sel_hi:[1,0]
	s_nop 0
	v_cvt_pk_bf16_f32 v184, v48, v49
	v_cvt_pk_bf16_f32 v185, v46, v47
	v_cvt_pk_bf16_f32 v186, v44, v45
	v_cvt_pk_bf16_f32 v187, v42, v43
	s_nop 0
	v_cvt_pk_bf16_f32 v208, v40, v41
	v_cvt_pk_bf16_f32 v209, v38, v39
	v_cvt_pk_bf16_f32 v210, v36, v37
	v_cvt_pk_bf16_f32 v211, v34, v35
	v_mov_b32_dpp v180, v184 row_ror:8 row_mask:0xf bank_mask:0xf
	v_mov_b32_dpp v181, v185 row_ror:8 row_mask:0xf bank_mask:0xf
	v_mov_b32_dpp v182, v186 row_ror:8 row_mask:0xf bank_mask:0xf
	v_mov_b32_dpp v183, v187 row_ror:8 row_mask:0xf bank_mask:0xf
	v_lshl_add_u64 v[212:213], v[174:175], 0, v[218:219]
	v_mov_b32_dpp v184, v208 row_ror:8 row_mask:0xf bank_mask:0xc
	v_mov_b32_dpp v185, v209 row_ror:8 row_mask:0xf bank_mask:0xc
	v_mov_b32_dpp v186, v210 row_ror:8 row_mask:0xf bank_mask:0xc
	v_mov_b32_dpp v187, v211 row_ror:8 row_mask:0xf bank_mask:0xc
	v_lshl_add_u64 v[214:215], v[174:175], 0, v[220:221]
	v_cndmask_b32_e32 v208, v180, v208, vcc
	v_cndmask_b32_e32 v209, v181, v209, vcc
	v_cndmask_b32_e32 v210, v182, v210, vcc
	v_cndmask_b32_e32 v211, v183, v211, vcc
	s_nop 0
	global_store_dwordx4 v[212:213], v[184:187], off
	global_store_dwordx4 v[214:215], v[208:211], off
	v_lshl_add_u64 v[174:175], v[174:175], 0, v[176:177]
	s_nop 1
	v_add_u32_e32 v35, 0xa0, v160
	v_mov_b32_e32 v34, v248
	s_nop 0
	v_pk_mul_f32 v[30:31], v[30:31], v[34:35] op_sel_hi:[1,0]
	v_pk_mul_f32 v[32:33], v[28:29], v[34:35] op_sel_hi:[1,0]
	v_pk_mul_f32 v[26:27], v[26:27], v[34:35] op_sel_hi:[1,0]
	v_pk_mul_f32 v[28:29], v[24:25], v[34:35] op_sel_hi:[1,0]
	v_pk_mul_f32 v[22:23], v[22:23], v[34:35] op_sel_hi:[1,0]
	v_pk_mul_f32 v[24:25], v[20:21], v[34:35] op_sel_hi:[1,0]
	v_pk_mul_f32 v[18:19], v[18:19], v[34:35] op_sel_hi:[1,0]
	v_pk_mul_f32 v[20:21], v[16:17], v[34:35] op_sel_hi:[1,0]
	s_nop 0
	v_cvt_pk_bf16_f32 v184, v32, v33
	v_cvt_pk_bf16_f32 v185, v30, v31
	v_cvt_pk_bf16_f32 v186, v28, v29
	v_cvt_pk_bf16_f32 v187, v26, v27
	s_nop 0
	v_cvt_pk_bf16_f32 v208, v24, v25
	v_cvt_pk_bf16_f32 v209, v22, v23
	v_cvt_pk_bf16_f32 v210, v20, v21
	v_cvt_pk_bf16_f32 v211, v18, v19
	v_mov_b32_dpp v180, v184 row_ror:8 row_mask:0xf bank_mask:0xf
	v_mov_b32_dpp v181, v185 row_ror:8 row_mask:0xf bank_mask:0xf
	v_mov_b32_dpp v182, v186 row_ror:8 row_mask:0xf bank_mask:0xf
	v_mov_b32_dpp v183, v187 row_ror:8 row_mask:0xf bank_mask:0xf
	v_lshl_add_u64 v[212:213], v[174:175], 0, v[218:219]
	v_mov_b32_dpp v184, v208 row_ror:8 row_mask:0xf bank_mask:0xc
	v_mov_b32_dpp v185, v209 row_ror:8 row_mask:0xf bank_mask:0xc
	v_mov_b32_dpp v186, v210 row_ror:8 row_mask:0xf bank_mask:0xc
	v_mov_b32_dpp v187, v211 row_ror:8 row_mask:0xf bank_mask:0xc
	v_lshl_add_u64 v[214:215], v[174:175], 0, v[220:221]
	v_cndmask_b32_e32 v208, v180, v208, vcc
	v_cndmask_b32_e32 v209, v181, v209, vcc
	v_cndmask_b32_e32 v210, v182, v210, vcc
	v_cndmask_b32_e32 v211, v183, v211, vcc
	s_nop 0
	global_store_dwordx4 v[212:213], v[184:187], off
	global_store_dwordx4 v[214:215], v[208:211], off
	v_lshl_add_u64 v[174:175], v[174:175], 0, v[176:177]
	s_nop 1
	v_add_u32_e32 v19, 0xb0, v160
	v_mov_b32_e32 v18, v249
	s_nop 0
	v_pk_mul_f32 v[14:15], v[14:15], v[18:19] op_sel_hi:[1,0]
	v_pk_mul_f32 v[16:17], v[12:13], v[18:19] op_sel_hi:[1,0]
	v_pk_mul_f32 v[10:11], v[10:11], v[18:19] op_sel_hi:[1,0]
	v_pk_mul_f32 v[12:13], v[8:9], v[18:19] op_sel_hi:[1,0]
	v_pk_mul_f32 v[6:7], v[6:7], v[18:19] op_sel_hi:[1,0]
	v_pk_mul_f32 v[8:9], v[4:5], v[18:19] op_sel_hi:[1,0]
	v_pk_mul_f32 v[2:3], v[2:3], v[18:19] op_sel_hi:[1,0]
	v_pk_mul_f32 v[4:5], v[0:1], v[18:19] op_sel_hi:[1,0]
	s_nop 0
	v_cvt_pk_bf16_f32 v184, v16, v17
	v_cvt_pk_bf16_f32 v185, v14, v15
	v_cvt_pk_bf16_f32 v186, v12, v13
	v_cvt_pk_bf16_f32 v187, v10, v11
	s_nop 0
	v_cvt_pk_bf16_f32 v208, v8, v9
	v_cvt_pk_bf16_f32 v209, v6, v7
	v_cvt_pk_bf16_f32 v210, v4, v5
	v_cvt_pk_bf16_f32 v211, v2, v3
	v_mov_b32_dpp v180, v184 row_ror:8 row_mask:0xf bank_mask:0xf
	v_mov_b32_dpp v181, v185 row_ror:8 row_mask:0xf bank_mask:0xf
	v_mov_b32_dpp v182, v186 row_ror:8 row_mask:0xf bank_mask:0xf
	v_mov_b32_dpp v183, v187 row_ror:8 row_mask:0xf bank_mask:0xf
	v_lshl_add_u64 v[212:213], v[174:175], 0, v[218:219]
	v_mov_b32_dpp v184, v208 row_ror:8 row_mask:0xf bank_mask:0xc
	v_mov_b32_dpp v185, v209 row_ror:8 row_mask:0xf bank_mask:0xc
	v_mov_b32_dpp v186, v210 row_ror:8 row_mask:0xf bank_mask:0xc
	v_mov_b32_dpp v187, v211 row_ror:8 row_mask:0xf bank_mask:0xc
	v_lshl_add_u64 v[214:215], v[174:175], 0, v[220:221]
	v_cndmask_b32_e32 v208, v180, v208, vcc
	v_cndmask_b32_e32 v209, v181, v209, vcc
	v_cndmask_b32_e32 v210, v182, v210, vcc
	v_cndmask_b32_e32 v211, v183, v211, vcc
	s_nop 0
	global_store_dwordx4 v[212:213], v[184:187], off
	global_store_dwordx4 v[214:215], v[208:211], off
	s_andn2_b64 vcc, exec, s[38:39]
	s_mov_b64 s[0:1], -1
	s_cbranch_vccnz .LBB0_350
	s_branch .LBB0_434
